# weight transposes: end-of-item wait reduced to lgkmcnt(0) (only the per-wave LDS scratch must be quiescent; stores drain in the background), on top of v15b
# baseline (speedup 1.0000x reference)
; __device__ __forceinline__ unsigned pk2(float lo, float hi) { f32x2 v = {lo, hi}; return __builtin_bit_cast(unsigned, __builtin_convertvector(v, bf16x2_hw)); }
;     ...
;     for (int it = it_lo; it < it_hi; it += it_st) {
;         const int kb = it / nblk, nb = it % nblk, k0 = 64 * kb, n0 = 64 * nb;
;         const int ng = n0 + n4; const int no = MAP ? win_map(ng) : ng;
;         const bool vec = MAP ? (no >= 0 && win_map(ng + 3) == no + 3) : true;
;         f32x4 v[16];
;         if (vec) {
; #pragma unroll
;             for (int i = 0; i < 16; ++i) { const float* p = W + (size_t)(k0 + 4 * i + ksub) * N_orig + no; if (MAP) { const f32x2 a0 = *(const f32x2*)p, a1 = *(const f32x2*)(p + 2); v[i] = (f32x4){a0.x, a0.y, a1.x, a1.y}; }
;                 else v[i] = __builtin_nontemporal_load((const f32x4*)p); }
;         } else {
; #pragma unroll
;             for (int i = 0; i < 16; ++i) { const float* p = W + (size_t)(k0 + 4 * i + ksub) * N_orig;
; #pragma unroll
;                 for (int e = 0; e < 4; ++e) { const int ne = MAP ? win_map(ng + e) : ng + e; v[i][e] = ne >= 0 ? p[ne] : 0.f; } }
;         }
;         if (kscale) {
; #pragma unroll
;             for (int i = 0; i < 16; ++i) v[i] *= kscale[k0 + 4 * i + ksub]; }
; #pragma unroll
;         for (int i = 0; i < 16; ++i) { float* d = scr + (4 * i + ksub) * 65 + n4; d[0] = v[i].x; d[1] = v[i].y; d[2] = v[i].z; d[3] = v[i].w; }
;         __builtin_amdgcn_s_waitcnt(0); asm volatile("" ::: "memory");
;         const int c = lane & 7;
; #pragma unroll
;         for (int j = 0; j < 8; ++j) { const int nn = (lane >> 3) + 8 * j; const float* sp = scr + (8 * c) * 65 + nn;
;             u32x4 o; o.x = pk2(sp[0 * 65], sp[1 * 65]); o.y = pk2(sp[2 * 65], sp[3 * 65]); o.z = pk2(sp[4 * 65], sp[5 * 65]); o.w = pk2(sp[6 * 65], sp[7 * 65]);
;             *(u32x4*)(WT + (size_t)(n0 + nn) * K + k0 + 8 * c) = o; }
;         __builtin_amdgcn_s_waitcnt(0); asm volatile("" ::: "memory");
;     }
.LBB0_11:
	v_add_u32_e32 v2, 0x410, v91
	s_waitcnt vmcnt(0)
	ds_write2_b32 v91, v4, v5 offset1:1
	ds_write2_b32 v91, v6, v7 offset0:2 offset1:3
	ds_write2_b32 v2, v8, v9 offset1:1
	v_add_u32_e32 v2, 0x418, v91
	ds_write2_b32 v2, v10, v11 offset1:1
	v_add_u32_e32 v2, 0x820, v91
	ds_write2_b32 v2, v12, v13 offset1:1
	v_add_u32_e32 v2, 0x828, v91
	ds_write2_b32 v2, v14, v15 offset1:1
	v_add_u32_e32 v2, 0xc30, v91
	ds_write2_b32 v2, v16, v17 offset1:1
	v_add_u32_e32 v2, 0xc38, v91
	ds_write2_b32 v2, v18, v19 offset1:1
	v_add_u32_e32 v2, 0x1040, v91
	ds_write2_b32 v2, v20, v21 offset1:1
	v_add_u32_e32 v2, 0x1048, v91
	ds_write2_b32 v2, v22, v23 offset1:1
	v_add_u32_e32 v2, 0x1450, v91
	ds_write2_b32 v2, v24, v25 offset1:1
	v_add_u32_e32 v2, 0x1458, v91
	ds_write2_b32 v2, v26, v27 offset1:1
	v_add_u32_e32 v2, 0x1860, v91
	ds_write2_b32 v2, v28, v29 offset1:1
	v_add_u32_e32 v2, 0x1868, v91
	ds_write2_b32 v2, v30, v31 offset1:1
	v_add_u32_e32 v2, 0x1c70, v91
	ds_write2_b32 v2, v32, v33 offset1:1
	v_add_u32_e32 v2, 0x1c78, v91
	ds_write2_b32 v2, v34, v35 offset1:1
	v_add_u32_e32 v2, 0x2080, v91
	ds_write2_b32 v2, v36, v37 offset1:1
	v_add_u32_e32 v2, 0x2088, v91
	ds_write2_b32 v2, v38, v39 offset1:1
	v_add_u32_e32 v2, 0x2490, v91
	ds_write2_b32 v2, v40, v41 offset1:1
	v_add_u32_e32 v2, 0x2498, v91
	ds_write2_b32 v2, v42, v43 offset1:1
	v_add_u32_e32 v2, 0x28a0, v91
	ds_write2_b32 v2, v44, v45 offset1:1
	v_add_u32_e32 v2, 0x28a8, v91
	ds_write2_b32 v2, v46, v47 offset1:1
	v_add_u32_e32 v2, 0x2cb0, v91
	ds_write2_b32 v2, v48, v49 offset1:1
	v_add_u32_e32 v2, 0x2cb8, v91
	ds_write2_b32 v2, v50, v51 offset1:1
	v_add_u32_e32 v2, 0x30c0, v91
	ds_write2_b32 v2, v52, v53 offset1:1
	v_add_u32_e32 v2, 0x30c8, v91
	ds_write2_b32 v2, v54, v55 offset1:1
	v_add_u32_e32 v2, 0x34d0, v91
	ds_write2_b32 v2, v56, v57 offset1:1
	v_add_u32_e32 v2, 0x34d8, v91
	ds_write2_b32 v2, v58, v59 offset1:1
	v_add_u32_e32 v2, 0x38e0, v91
	ds_write2_b32 v2, v60, v61 offset1:1
	v_add_u32_e32 v2, 0x38e8, v91
	ds_write2_b32 v2, v62, v63 offset1:1
	v_add_u32_e32 v2, 0x3cf0, v91
	ds_write2_b32 v2, v64, v65 offset1:1
	v_add_u32_e32 v2, 0x3cf8, v91
	ds_write2_b32 v2, v66, v67 offset1:1
	s_waitcnt vmcnt(0) expcnt(0) lgkmcnt(0)
	v_add_u32_e32 v2, 0x400, v83
	ds_read2_b32 v[8:9], v83 offset0:65 offset1:73
	ds_read2_b32 v[10:11], v83 offset1:8
	ds_read2_b32 v[12:13], v83 offset0:130 offset1:138
	ds_read2_b32 v[14:15], v83 offset0:195 offset1:203
	ds_read2_b32 v[16:17], v2 offset0:4 offset1:12
	ds_read2_b32 v[18:19], v2 offset0:69 offset1:77
	ds_read2_b32 v[20:21], v2 offset0:134 offset1:142
	ds_read2_b32 v[22:23], v2 offset0:199 offset1:207
	v_or_b32_e32 v26, v92, v82
	v_ashrrev_i32_e32 v71, 31, v70
	v_ashrrev_i32_e32 v27, 31, v26
	v_lshl_add_u64 v[24:25], v[70:71], 1, v[68:69]
	v_lshlrev_b64 v[26:27], 12, v[26:27]
	s_waitcnt lgkmcnt(6)
	v_cvt_pk_bf16_f32 v4, v10, v8
	s_waitcnt lgkmcnt(4)
	v_cvt_pk_bf16_f32 v5, v12, v14
	s_waitcnt lgkmcnt(2)
	v_cvt_pk_bf16_f32 v6, v16, v18
	s_waitcnt lgkmcnt(0)
	v_cvt_pk_bf16_f32 v7, v20, v22
	v_lshl_add_u64 v[26:27], v[24:25], 0, v[26:27]
	v_or_b32_e32 v8, v92, v84
	global_store_dwordx4 v[26:27], v[4:7], off
	v_add_u32_e32 v1, s28, v1
	s_movk_i32 s0, 0xcff
	v_cvt_pk_bf16_f32 v4, v11, v9
	v_ashrrev_i32_e32 v9, 31, v8
	v_cvt_pk_bf16_f32 v5, v13, v15
	v_cvt_pk_bf16_f32 v6, v17, v19
	v_cvt_pk_bf16_f32 v7, v21, v23
	v_lshlrev_b64 v[8:9], 12, v[8:9]
	ds_read2_b32 v[10:11], v83 offset0:81 offset1:89
	ds_read2_b32 v[12:13], v83 offset0:16 offset1:24
	ds_read2_b32 v[14:15], v83 offset0:146 offset1:154
	ds_read2_b32 v[16:17], v83 offset0:211 offset1:219
	ds_read2_b32 v[18:19], v2 offset0:20 offset1:28
	ds_read2_b32 v[20:21], v2 offset0:85 offset1:93
	ds_read2_b32 v[22:23], v2 offset0:150 offset1:158
	ds_read2_b32 v[26:27], v2 offset0:215 offset1:223
	v_lshl_add_u64 v[8:9], v[24:25], 0, v[8:9]
	global_store_dwordx4 v[8:9], v[4:7], off
	v_or_b32_e32 v8, v92, v85
	v_ashrrev_i32_e32 v9, 31, v8
	v_lshlrev_b64 v[8:9], 12, v[8:9]
	s_waitcnt lgkmcnt(6)
	v_cvt_pk_bf16_f32 v4, v12, v10
	s_waitcnt lgkmcnt(4)
	v_cvt_pk_bf16_f32 v5, v14, v16
	s_waitcnt lgkmcnt(2)
	v_cvt_pk_bf16_f32 v6, v18, v20
	s_waitcnt lgkmcnt(0)
	v_cvt_pk_bf16_f32 v7, v22, v26
	v_lshl_add_u64 v[8:9], v[24:25], 0, v[8:9]
	global_store_dwordx4 v[8:9], v[4:7], off
	v_or_b32_e32 v8, v92, v86
	v_ashrrev_i32_e32 v9, 31, v8
	v_cvt_pk_bf16_f32 v4, v13, v11
	v_cvt_pk_bf16_f32 v5, v15, v17
	v_cvt_pk_bf16_f32 v6, v19, v21
	v_cvt_pk_bf16_f32 v7, v23, v27
	v_lshlrev_b64 v[8:9], 12, v[8:9]
	ds_read2_b32 v[10:11], v83 offset0:32 offset1:40
	ds_read2_b32 v[12:13], v83 offset0:97 offset1:105
	ds_read2_b32 v[14:15], v83 offset0:162 offset1:170
	ds_read2_b32 v[16:17], v83 offset0:227 offset1:235
	ds_read2_b32 v[18:19], v2 offset0:36 offset1:44
	ds_read2_b32 v[20:21], v2 offset0:101 offset1:109
	ds_read2_b32 v[22:23], v2 offset0:166 offset1:174
	ds_read2_b32 v[26:27], v2 offset0:231 offset1:239
	v_lshl_add_u64 v[8:9], v[24:25], 0, v[8:9]
	global_store_dwordx4 v[8:9], v[4:7], off
	v_or_b32_e32 v8, v92, v87
	v_ashrrev_i32_e32 v9, 31, v8
	v_lshlrev_b64 v[8:9], 12, v[8:9]
	s_waitcnt lgkmcnt(6)
	v_cvt_pk_bf16_f32 v4, v10, v12
	s_waitcnt lgkmcnt(4)
	v_cvt_pk_bf16_f32 v5, v14, v16
	s_waitcnt lgkmcnt(2)
	v_cvt_pk_bf16_f32 v6, v18, v20
	s_waitcnt lgkmcnt(0)
	v_cvt_pk_bf16_f32 v7, v22, v26
	v_lshl_add_u64 v[8:9], v[24:25], 0, v[8:9]
	global_store_dwordx4 v[8:9], v[4:7], off
	v_or_b32_e32 v8, v92, v88
	v_ashrrev_i32_e32 v9, 31, v8
	v_cvt_pk_bf16_f32 v4, v11, v13
	v_cvt_pk_bf16_f32 v5, v15, v17
	v_cvt_pk_bf16_f32 v6, v19, v21
	v_cvt_pk_bf16_f32 v7, v23, v27
	v_lshlrev_b64 v[8:9], 12, v[8:9]
	ds_read2_b32 v[10:11], v83 offset0:48 offset1:56
	ds_read2_b32 v[12:13], v83 offset0:113 offset1:121
	ds_read2_b32 v[14:15], v83 offset0:178 offset1:186
	ds_read2_b32 v[16:17], v83 offset0:243 offset1:251
	ds_read2_b32 v[18:19], v2 offset0:52 offset1:60
	ds_read2_b32 v[20:21], v2 offset0:117 offset1:125
	ds_read2_b32 v[22:23], v2 offset0:182 offset1:190
	ds_read2_b32 v[26:27], v2 offset0:247 offset1:255
	v_lshl_add_u64 v[8:9], v[24:25], 0, v[8:9]
	global_store_dwordx4 v[8:9], v[4:7], off
	v_or_b32_e32 v8, v92, v89
	v_ashrrev_i32_e32 v9, 31, v8
	v_lshlrev_b64 v[8:9], 12, v[8:9]
	s_waitcnt lgkmcnt(6)
	v_cvt_pk_bf16_f32 v4, v10, v12
	s_waitcnt lgkmcnt(4)
	v_cvt_pk_bf16_f32 v5, v14, v16
	s_waitcnt lgkmcnt(2)
	v_cvt_pk_bf16_f32 v6, v18, v20
	s_waitcnt lgkmcnt(0)
	v_cvt_pk_bf16_f32 v7, v22, v26
	v_lshl_add_u64 v[8:9], v[24:25], 0, v[8:9]
	global_store_dwordx4 v[8:9], v[4:7], off
	v_or_b32_e32 v8, v92, v90
	v_ashrrev_i32_e32 v9, 31, v8
	v_lshlrev_b64 v[8:9], 12, v[8:9]
	v_cvt_pk_bf16_f32 v4, v11, v13
	v_cvt_pk_bf16_f32 v5, v15, v17
	v_cvt_pk_bf16_f32 v6, v19, v21
	v_cvt_pk_bf16_f32 v7, v23, v27
	v_lshl_add_u64 v[8:9], v[24:25], 0, v[8:9]
	global_store_dwordx4 v[8:9], v[4:7], off
	s_waitcnt lgkmcnt(0)
	v_cmp_lt_i32_e32 vcc, s0, v1
	s_or_b64 s[18:19], vcc, s[18:19]
	s_andn2_b64 exec, exec, s[18:19]
	s_cbranch_execz .LBB0_1072

;     ...
;         const int kb = it / nblk, nb = it % nblk, k0 = 64 * kb, n0 = 64 * nb;
;         const int ng = n0 + n4; const int no = MAP ? win_map(ng) : ng;
;         const bool vec = MAP ? (no >= 0 && win_map(ng + 3) == no + 3) : true;
;         f32x4 v[16];
;         if (vec) {
; #pragma unroll
;             for (int i = 0; i < 16; ++i) { const float* p = W + (size_t)(k0 + 4 * i + ksub) * N_orig + no; if (MAP) { const f32x2 a0 = *(const f32x2*)p, a1 = *(const f32x2*)(p + 2); v[i] = (f32x4){a0.x, a0.y, a1.x, a1.y}; }
;                 else v[i] = __builtin_nontemporal_load((const f32x4*)p); }
;         } else {
; #pragma unroll
;             for (int i = 0; i < 16; ++i) { const float* p = W + (size_t)(k0 + 4 * i + ksub) * N_orig;
; #pragma unroll
;                 for (int e = 0; e < 4; ++e) { const int ne = MAP ? win_map(ng + e) : ng + e; v[i][e] = ne >= 0 ? p[ne] : 0.f; } }
;         }
;         if (kscale) {
; #pragma unroll
;             for (int i = 0; i < 16; ++i) v[i] *= kscale[k0 + 4 * i + ksub]; }
; #pragma unroll
;         for (int i = 0; i < 16; ++i) { float* d = scr + (4 * i + ksub) * 65 + n4; d[0] = v[i].x; d[1] = v[i].y; d[2] = v[i].z; d[3] = v[i].w; }
.LBB0_1074:
	v_lshrrev_b32_e32 v4, 31, v1
	v_add_u32_e32 v4, v1, v4
	v_ashrrev_i32_e32 v4, 1, v4
	v_lshlrev_b32_e32 v66, 6, v4
	v_lshlrev_b32_e32 v73, 7, v4
	v_add_u32_e32 v4, v71, v69
	v_sub_u32_e32 v4, v4, v73
	v_or_b32_e32 v6, v66, v68
	v_ashrrev_i32_e32 v5, 31, v4
	v_ashrrev_i32_e32 v7, 31, v6
	v_lshl_add_u64 v[4:5], v[4:5], 2, s[6:7]
	v_lshlrev_b64 v[8:9], 9, v[6:7]
	v_lshl_add_u64 v[8:9], v[4:5], 0, v[8:9]
	global_load_dwordx4 v[74:77], v[8:9], off nt
	v_or_b32_e32 v8, 4, v6
	v_ashrrev_i32_e32 v9, 31, v8
	v_lshlrev_b64 v[8:9], 9, v[8:9]
	v_lshl_add_u64 v[8:9], v[4:5], 0, v[8:9]
	global_load_dwordx4 v[60:63], v[8:9], off nt
	v_or_b32_e32 v8, 8, v6
	v_ashrrev_i32_e32 v9, 31, v8
	v_lshlrev_b64 v[8:9], 9, v[8:9]
	v_lshl_add_u64 v[8:9], v[4:5], 0, v[8:9]
	global_load_dwordx4 v[56:59], v[8:9], off nt
	v_or_b32_e32 v8, 12, v6
	v_ashrrev_i32_e32 v9, 31, v8
	v_lshlrev_b64 v[8:9], 9, v[8:9]
	v_lshl_add_u64 v[8:9], v[4:5], 0, v[8:9]
	global_load_dwordx4 v[52:55], v[8:9], off nt
	v_or_b32_e32 v8, 16, v6
	v_ashrrev_i32_e32 v9, 31, v8
	v_lshlrev_b64 v[8:9], 9, v[8:9]
	v_lshl_add_u64 v[8:9], v[4:5], 0, v[8:9]
	global_load_dwordx4 v[48:51], v[8:9], off nt
	v_or_b32_e32 v8, 20, v6
	v_ashrrev_i32_e32 v9, 31, v8
	v_lshlrev_b64 v[8:9], 9, v[8:9]
	v_lshl_add_u64 v[8:9], v[4:5], 0, v[8:9]
	global_load_dwordx4 v[44:47], v[8:9], off nt
	v_or_b32_e32 v8, 24, v6
	v_ashrrev_i32_e32 v9, 31, v8
	v_lshlrev_b64 v[8:9], 9, v[8:9]
	v_lshl_add_u64 v[8:9], v[4:5], 0, v[8:9]
	global_load_dwordx4 v[40:43], v[8:9], off nt
	v_or_b32_e32 v8, 28, v6
	v_ashrrev_i32_e32 v9, 31, v8
	v_lshlrev_b64 v[8:9], 9, v[8:9]
	v_lshl_add_u64 v[8:9], v[4:5], 0, v[8:9]
	global_load_dwordx4 v[36:39], v[8:9], off nt
	v_or_b32_e32 v8, 32, v6
	v_ashrrev_i32_e32 v9, 31, v8
	v_lshlrev_b64 v[8:9], 9, v[8:9]
	v_lshl_add_u64 v[8:9], v[4:5], 0, v[8:9]
	global_load_dwordx4 v[32:35], v[8:9], off nt
	v_or_b32_e32 v8, 36, v6
	v_ashrrev_i32_e32 v9, 31, v8
	v_lshlrev_b64 v[8:9], 9, v[8:9]
	v_lshl_add_u64 v[8:9], v[4:5], 0, v[8:9]
	global_load_dwordx4 v[28:31], v[8:9], off nt
	v_or_b32_e32 v8, 40, v6
	v_ashrrev_i32_e32 v9, 31, v8
	v_lshlrev_b64 v[8:9], 9, v[8:9]
	v_lshl_add_u64 v[8:9], v[4:5], 0, v[8:9]
	global_load_dwordx4 v[24:27], v[8:9], off nt
	v_or_b32_e32 v8, 44, v6
	v_ashrrev_i32_e32 v9, 31, v8
	v_lshlrev_b64 v[8:9], 9, v[8:9]
	v_lshl_add_u64 v[8:9], v[4:5], 0, v[8:9]
	global_load_dwordx4 v[20:23], v[8:9], off nt
	v_or_b32_e32 v8, 48, v6
	v_ashrrev_i32_e32 v9, 31, v8
	v_lshlrev_b64 v[8:9], 9, v[8:9]
	v_lshl_add_u64 v[8:9], v[4:5], 0, v[8:9]
	global_load_dwordx4 v[16:19], v[8:9], off nt
	v_or_b32_e32 v8, 52, v6
	v_ashrrev_i32_e32 v9, 31, v8
	v_lshlrev_b64 v[8:9], 9, v[8:9]
	v_lshl_add_u64 v[8:9], v[4:5], 0, v[8:9]
	global_load_dwordx4 v[12:15], v[8:9], off nt
	v_or_b32_e32 v8, 56, v6
	v_ashrrev_i32_e32 v9, 31, v8
	v_lshlrev_b64 v[8:9], 9, v[8:9]
	v_or_b32_e32 v6, 60, v6
	v_lshl_add_u64 v[8:9], v[4:5], 0, v[8:9]
	v_ashrrev_i32_e32 v7, 31, v6
	global_load_dwordx4 v[8:11], v[8:9], off nt
	v_lshlrev_b64 v[6:7], 9, v[6:7]
	v_lshl_add_u64 v[4:5], v[4:5], 0, v[6:7]
	global_load_dwordx4 v[4:7], v[4:5], off nt
	v_add_u32_e32 v67, 0x410, v72
	s_waitcnt vmcnt(15)
	ds_write2_b32 v72, v74, v75 offset1:1
	ds_write2_b32 v72, v76, v77 offset0:2 offset1:3
	v_add_u32_e32 v1, s28, v1
	v_cmp_lt_i32_e32 vcc, s12, v1
	v_add_u32_e32 v69, s2, v69
	s_or_b64 s[8:9], vcc, s[8:9]
	s_waitcnt vmcnt(14)
	ds_write2_b32 v67, v60, v61 offset1:1
	v_add_u32_e32 v60, 0x418, v72
	ds_write2_b32 v60, v62, v63 offset1:1
	v_add_u32_e32 v60, 0x820, v72
	v_ashrrev_i32_e32 v67, 31, v66
	s_waitcnt vmcnt(13)
	ds_write2_b32 v60, v56, v57 offset1:1
	v_add_u32_e32 v56, 0x828, v72
	ds_write2_b32 v56, v58, v59 offset1:1
	v_add_u32_e32 v56, 0xc30, v72
	s_waitcnt vmcnt(12)
	ds_write2_b32 v56, v52, v53 offset1:1
	v_add_u32_e32 v52, 0xc38, v72
	ds_write2_b32 v52, v54, v55 offset1:1
	v_add_u32_e32 v52, 0x1040, v72
	s_waitcnt vmcnt(11)
	ds_write2_b32 v52, v48, v49 offset1:1
	v_add_u32_e32 v48, 0x1048, v72
	ds_write2_b32 v48, v50, v51 offset1:1
	v_add_u32_e32 v48, 0x1450, v72
	s_waitcnt vmcnt(10)
	ds_write2_b32 v48, v44, v45 offset1:1
	v_add_u32_e32 v44, 0x1458, v72
	ds_write2_b32 v44, v46, v47 offset1:1
	v_add_u32_e32 v44, 0x1860, v72
	s_waitcnt vmcnt(9)
	ds_write2_b32 v44, v40, v41 offset1:1
	v_add_u32_e32 v40, 0x1868, v72
	ds_write2_b32 v40, v42, v43 offset1:1
	v_add_u32_e32 v40, 0x1c70, v72
	s_waitcnt vmcnt(8)
	ds_write2_b32 v40, v36, v37 offset1:1
	v_add_u32_e32 v36, 0x1c78, v72
	ds_write2_b32 v36, v38, v39 offset1:1
	v_add_u32_e32 v36, 0x2080, v72
	s_waitcnt vmcnt(7)
	ds_write2_b32 v36, v32, v33 offset1:1
	v_add_u32_e32 v32, 0x2088, v72
	ds_write2_b32 v32, v34, v35 offset1:1
	v_add_u32_e32 v32, 0x2490, v72
	s_waitcnt vmcnt(6)
	ds_write2_b32 v32, v28, v29 offset1:1
	v_add_u32_e32 v28, 0x2498, v72
	ds_write2_b32 v28, v30, v31 offset1:1
	v_add_u32_e32 v28, 0x28a0, v72
	v_add_u32_e32 v30, 0x400, v2
	s_waitcnt vmcnt(5)
	ds_write2_b32 v28, v24, v25 offset1:1
	v_add_u32_e32 v24, 0x28a8, v72
	ds_write2_b32 v24, v26, v27 offset1:1
	v_add_u32_e32 v24, 0x2cb0, v72
	s_waitcnt vmcnt(4)
	ds_write2_b32 v24, v20, v21 offset1:1
	v_add_u32_e32 v20, 0x2cb8, v72
	ds_write2_b32 v20, v22, v23 offset1:1
	v_add_u32_e32 v20, 0x30c0, v72
	s_waitcnt vmcnt(3)
; __device__ __forceinline__ unsigned pk2(float lo, float hi) { f32x2 v = {lo, hi}; return __builtin_bit_cast(unsigned, __builtin_convertvector(v, bf16x2_hw)); }
;     ...
;         for (int i = 0; i < 16; ++i) { float* d = scr + (4 * i + ksub) * 65 + n4; d[0] = v[i].x; d[1] = v[i].y; d[2] = v[i].z; d[3] = v[i].w; }
;         __builtin_amdgcn_s_waitcnt(0); asm volatile("" ::: "memory");
;         const int c = lane & 7;
; #pragma unroll
;         for (int j = 0; j < 8; ++j) { const int nn = (lane >> 3) + 8 * j; const float* sp = scr + (8 * c) * 65 + nn;
;             u32x4 o; o.x = pk2(sp[0 * 65], sp[1 * 65]); o.y = pk2(sp[2 * 65], sp[3 * 65]); o.z = pk2(sp[4 * 65], sp[5 * 65]); o.w = pk2(sp[6 * 65], sp[7 * 65]);
;             *(u32x4*)(WT + (size_t)(n0 + nn) * K + k0 + 8 * c) = o; }
;         __builtin_amdgcn_s_waitcnt(0); asm volatile("" ::: "memory");
;     }
	ds_write2_b32 v20, v16, v17 offset1:1
	v_add_u32_e32 v16, 0x30c8, v72
	ds_write2_b32 v16, v18, v19 offset1:1
	v_add_u32_e32 v16, 0x34d0, v72
	s_waitcnt vmcnt(2)
	ds_write2_b32 v16, v12, v13 offset1:1
	v_add_u32_e32 v12, 0x34d8, v72
	ds_write2_b32 v12, v14, v15 offset1:1
	v_add_u32_e32 v12, 0x38e0, v72
	s_waitcnt vmcnt(1)
	ds_write2_b32 v12, v8, v9 offset1:1
	v_add_u32_e32 v8, 0x38e8, v72
	ds_write2_b32 v8, v10, v11 offset1:1
	v_add_u32_e32 v8, 0x3cf0, v72
	s_waitcnt vmcnt(0)
	ds_write2_b32 v8, v4, v5 offset1:1
	v_add_u32_e32 v4, 0x3cf8, v72
	ds_write2_b32 v4, v6, v7 offset1:1
	s_waitcnt vmcnt(0) expcnt(0) lgkmcnt(0)
	ds_read2_b32 v[10:11], v2 offset0:65 offset1:73
	ds_read2_b32 v[12:13], v2 offset1:8
	ds_read2_b32 v[14:15], v2 offset0:130 offset1:138
	ds_read2_b32 v[16:17], v2 offset0:195 offset1:203
	ds_read2_b32 v[18:19], v30 offset0:4 offset1:12
	ds_read2_b32 v[20:21], v30 offset0:69 offset1:77
	ds_read2_b32 v[22:23], v30 offset0:134 offset1:142
	ds_read2_b32 v[24:25], v30 offset0:199 offset1:207
	v_lshl_add_u64 v[8:9], v[66:67], 1, v[64:65]
	s_waitcnt lgkmcnt(6)
	v_cvt_pk_bf16_f32 v4, v12, v10
	v_add_u32_e32 v10, v71, v70
	v_sub_u32_e32 v26, v10, v73
	v_ashrrev_i32_e32 v27, 31, v26
	v_lshlrev_b64 v[28:29], 13, v[26:27]
	s_waitcnt lgkmcnt(4)
	v_cvt_pk_bf16_f32 v5, v14, v16
	s_waitcnt lgkmcnt(2)
	v_cvt_pk_bf16_f32 v6, v18, v20
	s_waitcnt lgkmcnt(0)
	v_cvt_pk_bf16_f32 v7, v22, v24
	v_lshl_add_u64 v[28:29], v[8:9], 0, v[28:29]
	v_add_u32_e32 v10, 8, v26
	global_store_dwordx4 v[28:29], v[4:7], off
	v_add_u32_e32 v28, 16, v26
	v_ashrrev_i32_e32 v29, 31, v28
	v_cvt_pk_bf16_f32 v4, v13, v11
	v_ashrrev_i32_e32 v11, 31, v10
	v_lshlrev_b64 v[10:11], 13, v[10:11]
	v_cvt_pk_bf16_f32 v5, v15, v17
	v_cvt_pk_bf16_f32 v6, v19, v21
	v_cvt_pk_bf16_f32 v7, v23, v25
	v_lshl_add_u64 v[10:11], v[8:9], 0, v[10:11]
	global_store_dwordx4 v[10:11], v[4:7], off
	ds_read2_b32 v[10:11], v2 offset0:81 offset1:89
	ds_read2_b32 v[12:13], v2 offset0:16 offset1:24
	ds_read2_b32 v[14:15], v2 offset0:146 offset1:154
	ds_read2_b32 v[16:17], v2 offset0:211 offset1:219
	ds_read2_b32 v[18:19], v30 offset0:20 offset1:28
	ds_read2_b32 v[20:21], v30 offset0:85 offset1:93
	ds_read2_b32 v[22:23], v30 offset0:150 offset1:158
	ds_read2_b32 v[24:25], v30 offset0:215 offset1:223
	v_lshlrev_b64 v[28:29], 13, v[28:29]
	s_waitcnt lgkmcnt(6)
	v_cvt_pk_bf16_f32 v4, v12, v10
	s_waitcnt lgkmcnt(4)
	v_cvt_pk_bf16_f32 v5, v14, v16
	s_waitcnt lgkmcnt(2)
	v_cvt_pk_bf16_f32 v6, v18, v20
	s_waitcnt lgkmcnt(0)
	v_cvt_pk_bf16_f32 v7, v22, v24
	v_lshl_add_u64 v[28:29], v[8:9], 0, v[28:29]
	v_add_u32_e32 v10, 24, v26
	global_store_dwordx4 v[28:29], v[4:7], off
	v_add_u32_e32 v28, 32, v26
	v_ashrrev_i32_e32 v29, 31, v28
	v_cvt_pk_bf16_f32 v4, v13, v11
	v_ashrrev_i32_e32 v11, 31, v10
	v_lshlrev_b64 v[10:11], 13, v[10:11]
	v_cvt_pk_bf16_f32 v5, v15, v17
	v_cvt_pk_bf16_f32 v6, v19, v21
	v_cvt_pk_bf16_f32 v7, v23, v25
	v_lshl_add_u64 v[10:11], v[8:9], 0, v[10:11]
	global_store_dwordx4 v[10:11], v[4:7], off
	ds_read2_b32 v[10:11], v2 offset0:32 offset1:40
	ds_read2_b32 v[12:13], v2 offset0:97 offset1:105
	ds_read2_b32 v[14:15], v2 offset0:162 offset1:170
	ds_read2_b32 v[16:17], v2 offset0:227 offset1:235
	ds_read2_b32 v[18:19], v30 offset0:36 offset1:44
	ds_read2_b32 v[20:21], v30 offset0:101 offset1:109
	ds_read2_b32 v[22:23], v30 offset0:166 offset1:174
	ds_read2_b32 v[24:25], v30 offset0:231 offset1:239
	v_lshlrev_b64 v[28:29], 13, v[28:29]
	s_waitcnt lgkmcnt(6)
	v_cvt_pk_bf16_f32 v4, v10, v12
	s_waitcnt lgkmcnt(4)
	v_cvt_pk_bf16_f32 v5, v14, v16
	s_waitcnt lgkmcnt(2)
	v_cvt_pk_bf16_f32 v6, v18, v20
	s_waitcnt lgkmcnt(0)
	v_cvt_pk_bf16_f32 v7, v22, v24
	v_lshl_add_u64 v[28:29], v[8:9], 0, v[28:29]
	v_add_u32_e32 v10, 40, v26
	global_store_dwordx4 v[28:29], v[4:7], off
	v_add_u32_e32 v28, 48, v26
	v_ashrrev_i32_e32 v29, 31, v28
	v_cvt_pk_bf16_f32 v4, v11, v13
	v_ashrrev_i32_e32 v11, 31, v10
	v_lshlrev_b64 v[10:11], 13, v[10:11]
	v_cvt_pk_bf16_f32 v5, v15, v17
	v_cvt_pk_bf16_f32 v6, v19, v21
	v_cvt_pk_bf16_f32 v7, v23, v25
	v_lshl_add_u64 v[10:11], v[8:9], 0, v[10:11]
	global_store_dwordx4 v[10:11], v[4:7], off
	ds_read2_b32 v[10:11], v2 offset0:48 offset1:56
	ds_read2_b32 v[12:13], v2 offset0:113 offset1:121
	ds_read2_b32 v[14:15], v2 offset0:178 offset1:186
	ds_read2_b32 v[16:17], v2 offset0:243 offset1:251
	ds_read2_b32 v[18:19], v30 offset0:52 offset1:60
	ds_read2_b32 v[20:21], v30 offset0:117 offset1:125
	ds_read2_b32 v[22:23], v30 offset0:182 offset1:190
	ds_read2_b32 v[24:25], v30 offset0:247 offset1:255
	v_lshlrev_b64 v[28:29], 13, v[28:29]
	s_waitcnt lgkmcnt(6)
	v_cvt_pk_bf16_f32 v4, v10, v12
	s_waitcnt lgkmcnt(4)
	v_cvt_pk_bf16_f32 v5, v14, v16
	s_waitcnt lgkmcnt(2)
	v_cvt_pk_bf16_f32 v6, v18, v20
	s_waitcnt lgkmcnt(0)
	v_cvt_pk_bf16_f32 v7, v22, v24
	v_lshl_add_u64 v[28:29], v[8:9], 0, v[28:29]
	v_add_u32_e32 v10, 56, v26
	global_store_dwordx4 v[28:29], v[4:7], off
	v_add_u32_e32 v70, s2, v70
	s_nop 0
	v_cvt_pk_bf16_f32 v4, v11, v13
	v_ashrrev_i32_e32 v11, 31, v10
	v_lshlrev_b64 v[10:11], 13, v[10:11]
	v_cvt_pk_bf16_f32 v5, v15, v17
	v_cvt_pk_bf16_f32 v6, v19, v21
	v_cvt_pk_bf16_f32 v7, v23, v25
	v_lshl_add_u64 v[8:9], v[8:9], 0, v[10:11]
	global_store_dwordx4 v[8:9], v[4:7], off
	s_waitcnt lgkmcnt(0)
	s_andn2_b64 exec, exec, s[8:9]
	s_cbranch_execnz .LBB0_1074

;     ...
;         const int kb = it / nblk, nb = it % nblk, k0 = 64 * kb, n0 = 64 * nb;
;         const int ng = n0 + n4; const int no = MAP ? win_map(ng) : ng;
;         const bool vec = MAP ? (no >= 0 && win_map(ng + 3) == no + 3) : true;
;         f32x4 v[16];
;         if (vec) {
; #pragma unroll
;             for (int i = 0; i < 16; ++i) { const float* p = W + (size_t)(k0 + 4 * i + ksub) * N_orig + no; if (MAP) { const f32x2 a0 = *(const f32x2*)p, a1 = *(const f32x2*)(p + 2); v[i] = (f32x4){a0.x, a0.y, a1.x, a1.y}; }
;                 else v[i] = __builtin_nontemporal_load((const f32x4*)p); }
;         } else {
; #pragma unroll
;             for (int i = 0; i < 16; ++i) { const float* p = W + (size_t)(k0 + 4 * i + ksub) * N_orig;
; #pragma unroll
;                 for (int e = 0; e < 4; ++e) { const int ne = MAP ? win_map(ng + e) : ng + e; v[i][e] = ne >= 0 ? p[ne] : 0.f; } }
;         }
;         if (kscale) {
; #pragma unroll
;             for (int i = 0; i < 16; ++i) v[i] *= kscale[k0 + 4 * i + ksub]; }
; #pragma unroll
;         for (int i = 0; i < 16; ++i) { float* d = scr + (4 * i + ksub) * 65 + n4; d[0] = v[i].x; d[1] = v[i].y; d[2] = v[i].z; d[3] = v[i].w; }
.LBB0_1080:
	v_lshrrev_b32_e32 v4, 31, v1
	v_add_u32_e32 v4, v1, v4
	v_ashrrev_i32_e32 v4, 1, v4
	v_lshlrev_b32_e32 v66, 6, v4
	v_lshlrev_b32_e32 v73, 7, v4
	v_add_u32_e32 v4, v71, v69
	v_sub_u32_e32 v4, v4, v73
	v_or_b32_e32 v6, v66, v68
	v_ashrrev_i32_e32 v5, 31, v4
	v_ashrrev_i32_e32 v7, 31, v6
	v_lshl_add_u64 v[4:5], v[4:5], 2, s[6:7]
	v_lshlrev_b64 v[8:9], 9, v[6:7]
	v_lshl_add_u64 v[8:9], v[4:5], 0, v[8:9]
	global_load_dwordx4 v[74:77], v[8:9], off nt
	v_or_b32_e32 v8, 4, v6
	v_ashrrev_i32_e32 v9, 31, v8
	v_lshlrev_b64 v[8:9], 9, v[8:9]
	v_lshl_add_u64 v[8:9], v[4:5], 0, v[8:9]
	global_load_dwordx4 v[60:63], v[8:9], off nt
	v_or_b32_e32 v8, 8, v6
	v_ashrrev_i32_e32 v9, 31, v8
	v_lshlrev_b64 v[8:9], 9, v[8:9]
	v_lshl_add_u64 v[8:9], v[4:5], 0, v[8:9]
	global_load_dwordx4 v[56:59], v[8:9], off nt
	v_or_b32_e32 v8, 12, v6
	v_ashrrev_i32_e32 v9, 31, v8
	v_lshlrev_b64 v[8:9], 9, v[8:9]
	v_lshl_add_u64 v[8:9], v[4:5], 0, v[8:9]
	global_load_dwordx4 v[52:55], v[8:9], off nt
	v_or_b32_e32 v8, 16, v6
	v_ashrrev_i32_e32 v9, 31, v8
	v_lshlrev_b64 v[8:9], 9, v[8:9]
	v_lshl_add_u64 v[8:9], v[4:5], 0, v[8:9]
	global_load_dwordx4 v[48:51], v[8:9], off nt
	v_or_b32_e32 v8, 20, v6
	v_ashrrev_i32_e32 v9, 31, v8
	v_lshlrev_b64 v[8:9], 9, v[8:9]
	v_lshl_add_u64 v[8:9], v[4:5], 0, v[8:9]
	global_load_dwordx4 v[44:47], v[8:9], off nt
	v_or_b32_e32 v8, 24, v6
	v_ashrrev_i32_e32 v9, 31, v8
	v_lshlrev_b64 v[8:9], 9, v[8:9]
	v_lshl_add_u64 v[8:9], v[4:5], 0, v[8:9]
	global_load_dwordx4 v[40:43], v[8:9], off nt
	v_or_b32_e32 v8, 28, v6
	v_ashrrev_i32_e32 v9, 31, v8
	v_lshlrev_b64 v[8:9], 9, v[8:9]
	v_lshl_add_u64 v[8:9], v[4:5], 0, v[8:9]
	global_load_dwordx4 v[36:39], v[8:9], off nt
	v_or_b32_e32 v8, 32, v6
	v_ashrrev_i32_e32 v9, 31, v8
	v_lshlrev_b64 v[8:9], 9, v[8:9]
	v_lshl_add_u64 v[8:9], v[4:5], 0, v[8:9]
	global_load_dwordx4 v[32:35], v[8:9], off nt
	v_or_b32_e32 v8, 36, v6
	v_ashrrev_i32_e32 v9, 31, v8
	v_lshlrev_b64 v[8:9], 9, v[8:9]
	v_lshl_add_u64 v[8:9], v[4:5], 0, v[8:9]
	global_load_dwordx4 v[28:31], v[8:9], off nt
	v_or_b32_e32 v8, 40, v6
	v_ashrrev_i32_e32 v9, 31, v8
	v_lshlrev_b64 v[8:9], 9, v[8:9]
	v_lshl_add_u64 v[8:9], v[4:5], 0, v[8:9]
	global_load_dwordx4 v[24:27], v[8:9], off nt
	v_or_b32_e32 v8, 44, v6
	v_ashrrev_i32_e32 v9, 31, v8
	v_lshlrev_b64 v[8:9], 9, v[8:9]
	v_lshl_add_u64 v[8:9], v[4:5], 0, v[8:9]
	global_load_dwordx4 v[20:23], v[8:9], off nt
	v_or_b32_e32 v8, 48, v6
	v_ashrrev_i32_e32 v9, 31, v8
	v_lshlrev_b64 v[8:9], 9, v[8:9]
	v_lshl_add_u64 v[8:9], v[4:5], 0, v[8:9]
	global_load_dwordx4 v[16:19], v[8:9], off nt
	v_or_b32_e32 v8, 52, v6
	v_ashrrev_i32_e32 v9, 31, v8
	v_lshlrev_b64 v[8:9], 9, v[8:9]
	v_lshl_add_u64 v[8:9], v[4:5], 0, v[8:9]
	global_load_dwordx4 v[12:15], v[8:9], off nt
	v_or_b32_e32 v8, 56, v6
	v_ashrrev_i32_e32 v9, 31, v8
	v_lshlrev_b64 v[8:9], 9, v[8:9]
	v_or_b32_e32 v6, 60, v6
	v_lshl_add_u64 v[8:9], v[4:5], 0, v[8:9]
	v_ashrrev_i32_e32 v7, 31, v6
	global_load_dwordx4 v[8:11], v[8:9], off nt
	v_lshlrev_b64 v[6:7], 9, v[6:7]
	v_lshl_add_u64 v[4:5], v[4:5], 0, v[6:7]
	global_load_dwordx4 v[4:7], v[4:5], off nt
	v_add_u32_e32 v67, 0x410, v72
	s_waitcnt vmcnt(15)
	ds_write2_b32 v72, v74, v75 offset1:1
	ds_write2_b32 v72, v76, v77 offset0:2 offset1:3
	v_add_u32_e32 v1, s28, v1
	v_cmp_lt_i32_e32 vcc, 3, v1
	v_add_u32_e32 v69, s2, v69
	s_or_b64 s[8:9], vcc, s[8:9]
	s_waitcnt vmcnt(14)
	ds_write2_b32 v67, v60, v61 offset1:1
	v_add_u32_e32 v60, 0x418, v72
	ds_write2_b32 v60, v62, v63 offset1:1
	v_add_u32_e32 v60, 0x820, v72
	v_ashrrev_i32_e32 v67, 31, v66
	s_waitcnt vmcnt(13)
	ds_write2_b32 v60, v56, v57 offset1:1
	v_add_u32_e32 v56, 0x828, v72
	ds_write2_b32 v56, v58, v59 offset1:1
	v_add_u32_e32 v56, 0xc30, v72
	s_waitcnt vmcnt(12)
	ds_write2_b32 v56, v52, v53 offset1:1
	v_add_u32_e32 v52, 0xc38, v72
	ds_write2_b32 v52, v54, v55 offset1:1
	v_add_u32_e32 v52, 0x1040, v72
	s_waitcnt vmcnt(11)
	ds_write2_b32 v52, v48, v49 offset1:1
	v_add_u32_e32 v48, 0x1048, v72
	ds_write2_b32 v48, v50, v51 offset1:1
	v_add_u32_e32 v48, 0x1450, v72
	s_waitcnt vmcnt(10)
	ds_write2_b32 v48, v44, v45 offset1:1
	v_add_u32_e32 v44, 0x1458, v72
	ds_write2_b32 v44, v46, v47 offset1:1
	v_add_u32_e32 v44, 0x1860, v72
	s_waitcnt vmcnt(9)
	ds_write2_b32 v44, v40, v41 offset1:1
	v_add_u32_e32 v40, 0x1868, v72
	ds_write2_b32 v40, v42, v43 offset1:1
	v_add_u32_e32 v40, 0x1c70, v72
	s_waitcnt vmcnt(8)
	ds_write2_b32 v40, v36, v37 offset1:1
	v_add_u32_e32 v36, 0x1c78, v72
	ds_write2_b32 v36, v38, v39 offset1:1
	v_add_u32_e32 v36, 0x2080, v72
	s_waitcnt vmcnt(7)
	ds_write2_b32 v36, v32, v33 offset1:1
	v_add_u32_e32 v32, 0x2088, v72
	ds_write2_b32 v32, v34, v35 offset1:1
	v_add_u32_e32 v32, 0x2490, v72
	s_waitcnt vmcnt(6)
	ds_write2_b32 v32, v28, v29 offset1:1
	v_add_u32_e32 v28, 0x2498, v72
	ds_write2_b32 v28, v30, v31 offset1:1
	v_add_u32_e32 v28, 0x28a0, v72
	v_add_u32_e32 v30, 0x400, v2
	s_waitcnt vmcnt(5)
	ds_write2_b32 v28, v24, v25 offset1:1
	v_add_u32_e32 v24, 0x28a8, v72
	ds_write2_b32 v24, v26, v27 offset1:1
	v_add_u32_e32 v24, 0x2cb0, v72
	s_waitcnt vmcnt(4)
	ds_write2_b32 v24, v20, v21 offset1:1
	v_add_u32_e32 v20, 0x2cb8, v72
	ds_write2_b32 v20, v22, v23 offset1:1
	v_add_u32_e32 v20, 0x30c0, v72
	s_waitcnt vmcnt(3)
; __device__ __forceinline__ unsigned pk2(float lo, float hi) { f32x2 v = {lo, hi}; return __builtin_bit_cast(unsigned, __builtin_convertvector(v, bf16x2_hw)); }
;     ...
;         for (int i = 0; i < 16; ++i) { float* d = scr + (4 * i + ksub) * 65 + n4; d[0] = v[i].x; d[1] = v[i].y; d[2] = v[i].z; d[3] = v[i].w; }
;         __builtin_amdgcn_s_waitcnt(0); asm volatile("" ::: "memory");
;         const int c = lane & 7;
; #pragma unroll
;         for (int j = 0; j < 8; ++j) { const int nn = (lane >> 3) + 8 * j; const float* sp = scr + (8 * c) * 65 + nn;
;             u32x4 o; o.x = pk2(sp[0 * 65], sp[1 * 65]); o.y = pk2(sp[2 * 65], sp[3 * 65]); o.z = pk2(sp[4 * 65], sp[5 * 65]); o.w = pk2(sp[6 * 65], sp[7 * 65]);
;             *(u32x4*)(WT + (size_t)(n0 + nn) * K + k0 + 8 * c) = o; }
;         __builtin_amdgcn_s_waitcnt(0); asm volatile("" ::: "memory");
;     }
	ds_write2_b32 v20, v16, v17 offset1:1
	v_add_u32_e32 v16, 0x30c8, v72
	ds_write2_b32 v16, v18, v19 offset1:1
	v_add_u32_e32 v16, 0x34d0, v72
	s_waitcnt vmcnt(2)
	ds_write2_b32 v16, v12, v13 offset1:1
	v_add_u32_e32 v12, 0x34d8, v72
	ds_write2_b32 v12, v14, v15 offset1:1
	v_add_u32_e32 v12, 0x38e0, v72
	s_waitcnt vmcnt(1)
	ds_write2_b32 v12, v8, v9 offset1:1
	v_add_u32_e32 v8, 0x38e8, v72
	ds_write2_b32 v8, v10, v11 offset1:1
	v_add_u32_e32 v8, 0x3cf0, v72
	s_waitcnt vmcnt(0)
	ds_write2_b32 v8, v4, v5 offset1:1
	v_add_u32_e32 v4, 0x3cf8, v72
	ds_write2_b32 v4, v6, v7 offset1:1
	s_waitcnt vmcnt(0) expcnt(0) lgkmcnt(0)
	ds_read2_b32 v[10:11], v2 offset0:65 offset1:73
	ds_read2_b32 v[12:13], v2 offset1:8
	ds_read2_b32 v[14:15], v2 offset0:130 offset1:138
	ds_read2_b32 v[16:17], v2 offset0:195 offset1:203
	ds_read2_b32 v[18:19], v30 offset0:4 offset1:12
	ds_read2_b32 v[20:21], v30 offset0:69 offset1:77
	ds_read2_b32 v[22:23], v30 offset0:134 offset1:142
	ds_read2_b32 v[24:25], v30 offset0:199 offset1:207
	v_lshl_add_u64 v[8:9], v[66:67], 1, v[64:65]
	s_waitcnt lgkmcnt(6)
	v_cvt_pk_bf16_f32 v4, v12, v10
	v_add_u32_e32 v10, v71, v70
	v_sub_u32_e32 v26, v10, v73
	v_ashrrev_i32_e32 v27, 31, v26
	v_lshlrev_b64 v[28:29], 8, v[26:27]
	s_waitcnt lgkmcnt(4)
	v_cvt_pk_bf16_f32 v5, v14, v16
	s_waitcnt lgkmcnt(2)
	v_cvt_pk_bf16_f32 v6, v18, v20
	s_waitcnt lgkmcnt(0)
	v_cvt_pk_bf16_f32 v7, v22, v24
	v_lshl_add_u64 v[28:29], v[8:9], 0, v[28:29]
	v_add_u32_e32 v10, 8, v26
	global_store_dwordx4 v[28:29], v[4:7], off
	v_add_u32_e32 v28, 16, v26
	v_ashrrev_i32_e32 v29, 31, v28
	v_cvt_pk_bf16_f32 v4, v13, v11
	v_ashrrev_i32_e32 v11, 31, v10
	v_lshlrev_b64 v[10:11], 8, v[10:11]
	v_cvt_pk_bf16_f32 v5, v15, v17
	v_cvt_pk_bf16_f32 v6, v19, v21
	v_cvt_pk_bf16_f32 v7, v23, v25
	v_lshl_add_u64 v[10:11], v[8:9], 0, v[10:11]
	global_store_dwordx4 v[10:11], v[4:7], off
	ds_read2_b32 v[10:11], v2 offset0:81 offset1:89
	ds_read2_b32 v[12:13], v2 offset0:16 offset1:24
	ds_read2_b32 v[14:15], v2 offset0:146 offset1:154
	ds_read2_b32 v[16:17], v2 offset0:211 offset1:219
	ds_read2_b32 v[18:19], v30 offset0:20 offset1:28
	ds_read2_b32 v[20:21], v30 offset0:85 offset1:93
	ds_read2_b32 v[22:23], v30 offset0:150 offset1:158
	ds_read2_b32 v[24:25], v30 offset0:215 offset1:223
	v_lshlrev_b64 v[28:29], 8, v[28:29]
	s_waitcnt lgkmcnt(6)
	v_cvt_pk_bf16_f32 v4, v12, v10
	s_waitcnt lgkmcnt(4)
	v_cvt_pk_bf16_f32 v5, v14, v16
	s_waitcnt lgkmcnt(2)
	v_cvt_pk_bf16_f32 v6, v18, v20
	s_waitcnt lgkmcnt(0)
	v_cvt_pk_bf16_f32 v7, v22, v24
	v_lshl_add_u64 v[28:29], v[8:9], 0, v[28:29]
	v_add_u32_e32 v10, 24, v26
	global_store_dwordx4 v[28:29], v[4:7], off
	v_add_u32_e32 v28, 32, v26
	v_ashrrev_i32_e32 v29, 31, v28
	v_cvt_pk_bf16_f32 v4, v13, v11
	v_ashrrev_i32_e32 v11, 31, v10
	v_lshlrev_b64 v[10:11], 8, v[10:11]
	v_cvt_pk_bf16_f32 v5, v15, v17
	v_cvt_pk_bf16_f32 v6, v19, v21
	v_cvt_pk_bf16_f32 v7, v23, v25
	v_lshl_add_u64 v[10:11], v[8:9], 0, v[10:11]
	global_store_dwordx4 v[10:11], v[4:7], off
	ds_read2_b32 v[10:11], v2 offset0:32 offset1:40
	ds_read2_b32 v[12:13], v2 offset0:97 offset1:105
	ds_read2_b32 v[14:15], v2 offset0:162 offset1:170
	ds_read2_b32 v[16:17], v2 offset0:227 offset1:235
	ds_read2_b32 v[18:19], v30 offset0:36 offset1:44
	ds_read2_b32 v[20:21], v30 offset0:101 offset1:109
	ds_read2_b32 v[22:23], v30 offset0:166 offset1:174
	ds_read2_b32 v[24:25], v30 offset0:231 offset1:239
	v_lshlrev_b64 v[28:29], 8, v[28:29]
	s_waitcnt lgkmcnt(6)
	v_cvt_pk_bf16_f32 v4, v10, v12
	s_waitcnt lgkmcnt(4)
	v_cvt_pk_bf16_f32 v5, v14, v16
	s_waitcnt lgkmcnt(2)
	v_cvt_pk_bf16_f32 v6, v18, v20
	s_waitcnt lgkmcnt(0)
	v_cvt_pk_bf16_f32 v7, v22, v24
	v_lshl_add_u64 v[28:29], v[8:9], 0, v[28:29]
	v_add_u32_e32 v10, 40, v26
	global_store_dwordx4 v[28:29], v[4:7], off
	v_add_u32_e32 v28, 48, v26
	v_ashrrev_i32_e32 v29, 31, v28
	v_cvt_pk_bf16_f32 v4, v11, v13
	v_ashrrev_i32_e32 v11, 31, v10
	v_lshlrev_b64 v[10:11], 8, v[10:11]
	v_cvt_pk_bf16_f32 v5, v15, v17
	v_cvt_pk_bf16_f32 v6, v19, v21
	v_cvt_pk_bf16_f32 v7, v23, v25
	v_lshl_add_u64 v[10:11], v[8:9], 0, v[10:11]
	global_store_dwordx4 v[10:11], v[4:7], off
	ds_read2_b32 v[10:11], v2 offset0:48 offset1:56
	ds_read2_b32 v[12:13], v2 offset0:113 offset1:121
	ds_read2_b32 v[14:15], v2 offset0:178 offset1:186
	ds_read2_b32 v[16:17], v2 offset0:243 offset1:251
	ds_read2_b32 v[18:19], v30 offset0:52 offset1:60
	ds_read2_b32 v[20:21], v30 offset0:117 offset1:125
	ds_read2_b32 v[22:23], v30 offset0:182 offset1:190
	ds_read2_b32 v[24:25], v30 offset0:247 offset1:255
	v_lshlrev_b64 v[28:29], 8, v[28:29]
	s_waitcnt lgkmcnt(6)
	v_cvt_pk_bf16_f32 v4, v10, v12
	s_waitcnt lgkmcnt(4)
	v_cvt_pk_bf16_f32 v5, v14, v16
	s_waitcnt lgkmcnt(2)
	v_cvt_pk_bf16_f32 v6, v18, v20
	s_waitcnt lgkmcnt(0)
	v_cvt_pk_bf16_f32 v7, v22, v24
	v_lshl_add_u64 v[28:29], v[8:9], 0, v[28:29]
	v_add_u32_e32 v10, 56, v26
	global_store_dwordx4 v[28:29], v[4:7], off
	v_add_u32_e32 v70, s2, v70
	s_nop 0
	v_cvt_pk_bf16_f32 v4, v11, v13
	v_ashrrev_i32_e32 v11, 31, v10
	v_lshlrev_b64 v[10:11], 8, v[10:11]
	v_cvt_pk_bf16_f32 v5, v15, v17
	v_cvt_pk_bf16_f32 v6, v19, v21
	v_cvt_pk_bf16_f32 v7, v23, v25
	v_lshl_add_u64 v[8:9], v[8:9], 0, v[10:11]
	global_store_dwordx4 v[8:9], v[4:7], off
	s_waitcnt lgkmcnt(0)
	s_andn2_b64 exec, exec, s[8:9]
	s_cbranch_execnz .LBB0_1080

;     ...
;     for (int it = it_lo; it < it_hi; it += it_st) {
;         const int kb = it / nblk, nb = it % nblk, k0 = 64 * kb, n0 = 64 * nb;
;         const int ng = n0 + n4; const int no = MAP ? win_map(ng) : ng;
;         const bool vec = MAP ? (no >= 0 && win_map(ng + 3) == no + 3) : true;
;         f32x4 v[16];
;         if (vec) {
; #pragma unroll
;             for (int i = 0; i < 16; ++i) { const float* p = W + (size_t)(k0 + 4 * i + ksub) * N_orig + no; if (MAP) { const f32x2 a0 = *(const f32x2*)p, a1 = *(const f32x2*)(p + 2); v[i] = (f32x4){a0.x, a0.y, a1.x, a1.y}; }
;                 else v[i] = __builtin_nontemporal_load((const f32x4*)p); }
;         } else {
; #pragma unroll
;             for (int i = 0; i < 16; ++i) { const float* p = W + (size_t)(k0 + 4 * i + ksub) * N_orig;
; #pragma unroll
;                 for (int e = 0; e < 4; ++e) { const int ne = MAP ? win_map(ng + e) : ng + e; v[i][e] = ne >= 0 ? p[ne] : 0.f; } }
;         }
;         if (kscale) {
; #pragma unroll
;             for (int i = 0; i < 16; ++i) v[i] *= kscale[k0 + 4 * i + ksub]; }
; #pragma unroll
;         for (int i = 0; i < 16; ++i) { float* d = scr + (4 * i + ksub) * 65 + n4; d[0] = v[i].x; d[1] = v[i].y; d[2] = v[i].z; d[3] = v[i].w; }
.LBB0_1882:
	v_ashrrev_i32_e32 v4, 31, v1
	v_lshrrev_b32_e32 v4, 27, v4
	v_add_u32_e32 v4, v1, v4
	v_ashrrev_i32_e32 v4, 5, v4
	v_lshlrev_b32_e32 v66, 6, v4
	v_lshlrev_b32_e32 v73, 11, v4
	v_add_u32_e32 v4, v71, v69
	v_sub_u32_e32 v4, v4, v73
	v_or_b32_e32 v6, v66, v68
	v_ashrrev_i32_e32 v5, 31, v4
	v_ashrrev_i32_e32 v7, 31, v6
	v_lshl_add_u64 v[4:5], v[4:5], 2, s[10:11]
	v_lshlrev_b64 v[8:9], 13, v[6:7]
	v_lshl_add_u64 v[8:9], v[4:5], 0, v[8:9]
	global_load_dwordx4 v[74:77], v[8:9], off nt
	v_or_b32_e32 v8, 4, v6
	v_ashrrev_i32_e32 v9, 31, v8
	v_lshlrev_b64 v[8:9], 13, v[8:9]
	v_lshl_add_u64 v[8:9], v[4:5], 0, v[8:9]
	global_load_dwordx4 v[60:63], v[8:9], off nt
	v_or_b32_e32 v8, 8, v6
	v_ashrrev_i32_e32 v9, 31, v8
	v_lshlrev_b64 v[8:9], 13, v[8:9]
	v_lshl_add_u64 v[8:9], v[4:5], 0, v[8:9]
	global_load_dwordx4 v[56:59], v[8:9], off nt
	v_or_b32_e32 v8, 12, v6
	v_ashrrev_i32_e32 v9, 31, v8
	v_lshlrev_b64 v[8:9], 13, v[8:9]
	v_lshl_add_u64 v[8:9], v[4:5], 0, v[8:9]
	global_load_dwordx4 v[52:55], v[8:9], off nt
	v_or_b32_e32 v8, 16, v6
	v_ashrrev_i32_e32 v9, 31, v8
	v_lshlrev_b64 v[8:9], 13, v[8:9]
	v_lshl_add_u64 v[8:9], v[4:5], 0, v[8:9]
	global_load_dwordx4 v[48:51], v[8:9], off nt
	v_or_b32_e32 v8, 20, v6
	v_ashrrev_i32_e32 v9, 31, v8
	v_lshlrev_b64 v[8:9], 13, v[8:9]
	v_lshl_add_u64 v[8:9], v[4:5], 0, v[8:9]
	global_load_dwordx4 v[44:47], v[8:9], off nt
	v_or_b32_e32 v8, 24, v6
	v_ashrrev_i32_e32 v9, 31, v8
	v_lshlrev_b64 v[8:9], 13, v[8:9]
	v_lshl_add_u64 v[8:9], v[4:5], 0, v[8:9]
	global_load_dwordx4 v[40:43], v[8:9], off nt
	v_or_b32_e32 v8, 28, v6
	v_ashrrev_i32_e32 v9, 31, v8
	v_lshlrev_b64 v[8:9], 13, v[8:9]
	v_lshl_add_u64 v[8:9], v[4:5], 0, v[8:9]
	global_load_dwordx4 v[36:39], v[8:9], off nt
	v_or_b32_e32 v8, 32, v6
	v_ashrrev_i32_e32 v9, 31, v8
	v_lshlrev_b64 v[8:9], 13, v[8:9]
	v_lshl_add_u64 v[8:9], v[4:5], 0, v[8:9]
	global_load_dwordx4 v[32:35], v[8:9], off nt
	v_or_b32_e32 v8, 36, v6
	v_ashrrev_i32_e32 v9, 31, v8
	v_lshlrev_b64 v[8:9], 13, v[8:9]
	v_lshl_add_u64 v[8:9], v[4:5], 0, v[8:9]
	global_load_dwordx4 v[28:31], v[8:9], off nt
	v_or_b32_e32 v8, 40, v6
	v_ashrrev_i32_e32 v9, 31, v8
	v_lshlrev_b64 v[8:9], 13, v[8:9]
	v_lshl_add_u64 v[8:9], v[4:5], 0, v[8:9]
	global_load_dwordx4 v[24:27], v[8:9], off nt
	v_or_b32_e32 v8, 44, v6
	v_ashrrev_i32_e32 v9, 31, v8
	v_lshlrev_b64 v[8:9], 13, v[8:9]
	v_lshl_add_u64 v[8:9], v[4:5], 0, v[8:9]
	global_load_dwordx4 v[20:23], v[8:9], off nt
	v_or_b32_e32 v8, 48, v6
	v_ashrrev_i32_e32 v9, 31, v8
	v_lshlrev_b64 v[8:9], 13, v[8:9]
	v_lshl_add_u64 v[8:9], v[4:5], 0, v[8:9]
	global_load_dwordx4 v[16:19], v[8:9], off nt
	v_or_b32_e32 v8, 52, v6
	v_ashrrev_i32_e32 v9, 31, v8
	v_lshlrev_b64 v[8:9], 13, v[8:9]
	v_lshl_add_u64 v[8:9], v[4:5], 0, v[8:9]
	global_load_dwordx4 v[12:15], v[8:9], off nt
	v_or_b32_e32 v8, 56, v6
	v_ashrrev_i32_e32 v9, 31, v8
	v_lshlrev_b64 v[8:9], 13, v[8:9]
	v_or_b32_e32 v6, 60, v6
	v_lshl_add_u64 v[8:9], v[4:5], 0, v[8:9]
	v_ashrrev_i32_e32 v7, 31, v6
	global_load_dwordx4 v[8:11], v[8:9], off nt
	v_lshlrev_b64 v[6:7], 13, v[6:7]
	v_lshl_add_u64 v[4:5], v[4:5], 0, v[6:7]
	global_load_dwordx4 v[4:7], v[4:5], off nt
	v_add_u32_e32 v67, 0x410, v72
	s_waitcnt vmcnt(15)
	ds_write2_b32 v72, v74, v75 offset1:1
	ds_write2_b32 v72, v76, v77 offset0:2 offset1:3
	v_add_u32_e32 v1, 8, v1
	v_cmp_le_i32_e32 vcc, s3, v1
	v_add_u32_e32 v69, 0x200, v69
	s_or_b64 s[12:13], vcc, s[12:13]
	s_waitcnt vmcnt(14)
	ds_write2_b32 v67, v60, v61 offset1:1
	v_add_u32_e32 v60, 0x418, v72
	ds_write2_b32 v60, v62, v63 offset1:1
	v_add_u32_e32 v60, 0x820, v72
	v_ashrrev_i32_e32 v67, 31, v66
	s_waitcnt vmcnt(13)
	ds_write2_b32 v60, v56, v57 offset1:1
	v_add_u32_e32 v56, 0x828, v72
	ds_write2_b32 v56, v58, v59 offset1:1
	v_add_u32_e32 v56, 0xc30, v72
	s_waitcnt vmcnt(12)
	ds_write2_b32 v56, v52, v53 offset1:1
	v_add_u32_e32 v52, 0xc38, v72
	ds_write2_b32 v52, v54, v55 offset1:1
	v_add_u32_e32 v52, 0x1040, v72
	s_waitcnt vmcnt(11)
	ds_write2_b32 v52, v48, v49 offset1:1
	v_add_u32_e32 v48, 0x1048, v72
	ds_write2_b32 v48, v50, v51 offset1:1
	v_add_u32_e32 v48, 0x1450, v72
	s_waitcnt vmcnt(10)
	ds_write2_b32 v48, v44, v45 offset1:1
	v_add_u32_e32 v44, 0x1458, v72
	ds_write2_b32 v44, v46, v47 offset1:1
	v_add_u32_e32 v44, 0x1860, v72
	s_waitcnt vmcnt(9)
	ds_write2_b32 v44, v40, v41 offset1:1
	v_add_u32_e32 v40, 0x1868, v72
	ds_write2_b32 v40, v42, v43 offset1:1
	v_add_u32_e32 v40, 0x1c70, v72
	s_waitcnt vmcnt(8)
	ds_write2_b32 v40, v36, v37 offset1:1
	v_add_u32_e32 v36, 0x1c78, v72
	ds_write2_b32 v36, v38, v39 offset1:1
	v_add_u32_e32 v36, 0x2080, v72
	s_waitcnt vmcnt(7)
	ds_write2_b32 v36, v32, v33 offset1:1
	v_add_u32_e32 v32, 0x2088, v72
	ds_write2_b32 v32, v34, v35 offset1:1
	v_add_u32_e32 v32, 0x2490, v72
	s_waitcnt vmcnt(6)
	ds_write2_b32 v32, v28, v29 offset1:1
	v_add_u32_e32 v28, 0x2498, v72
	ds_write2_b32 v28, v30, v31 offset1:1
	v_add_u32_e32 v28, 0x28a0, v72
	v_add_u32_e32 v30, 0x400, v2
	s_waitcnt vmcnt(5)
	ds_write2_b32 v28, v24, v25 offset1:1
	v_add_u32_e32 v24, 0x28a8, v72
	ds_write2_b32 v24, v26, v27 offset1:1
	v_add_u32_e32 v24, 0x2cb0, v72
	s_waitcnt vmcnt(4)
	ds_write2_b32 v24, v20, v21 offset1:1
	v_add_u32_e32 v20, 0x2cb8, v72
	ds_write2_b32 v20, v22, v23 offset1:1
	v_add_u32_e32 v20, 0x30c0, v72
	s_waitcnt vmcnt(3)
; __device__ __forceinline__ unsigned pk2(float lo, float hi) { f32x2 v = {lo, hi}; return __builtin_bit_cast(unsigned, __builtin_convertvector(v, bf16x2_hw)); }
;     ...
;         for (int i = 0; i < 16; ++i) { float* d = scr + (4 * i + ksub) * 65 + n4; d[0] = v[i].x; d[1] = v[i].y; d[2] = v[i].z; d[3] = v[i].w; }
;         __builtin_amdgcn_s_waitcnt(0); asm volatile("" ::: "memory");
;         const int c = lane & 7;
; #pragma unroll
;         for (int j = 0; j < 8; ++j) { const int nn = (lane >> 3) + 8 * j; const float* sp = scr + (8 * c) * 65 + nn;
;             u32x4 o; o.x = pk2(sp[0 * 65], sp[1 * 65]); o.y = pk2(sp[2 * 65], sp[3 * 65]); o.z = pk2(sp[4 * 65], sp[5 * 65]); o.w = pk2(sp[6 * 65], sp[7 * 65]);
;             *(u32x4*)(WT + (size_t)(n0 + nn) * K + k0 + 8 * c) = o; }
;         __builtin_amdgcn_s_waitcnt(0); asm volatile("" ::: "memory");
;     }
	ds_write2_b32 v20, v16, v17 offset1:1
	v_add_u32_e32 v16, 0x30c8, v72
	ds_write2_b32 v16, v18, v19 offset1:1
	v_add_u32_e32 v16, 0x34d0, v72
	s_waitcnt vmcnt(2)
	ds_write2_b32 v16, v12, v13 offset1:1
	v_add_u32_e32 v12, 0x34d8, v72
	ds_write2_b32 v12, v14, v15 offset1:1
	v_add_u32_e32 v12, 0x38e0, v72
	s_waitcnt vmcnt(1)
	ds_write2_b32 v12, v8, v9 offset1:1
	v_add_u32_e32 v8, 0x38e8, v72
	ds_write2_b32 v8, v10, v11 offset1:1
	v_add_u32_e32 v8, 0x3cf0, v72
	s_waitcnt vmcnt(0)
	ds_write2_b32 v8, v4, v5 offset1:1
	v_add_u32_e32 v4, 0x3cf8, v72
	ds_write2_b32 v4, v6, v7 offset1:1
	s_waitcnt vmcnt(0) expcnt(0) lgkmcnt(0)
	ds_read2_b32 v[10:11], v2 offset0:65 offset1:73
	ds_read2_b32 v[12:13], v2 offset1:8
	ds_read2_b32 v[14:15], v2 offset0:130 offset1:138
	ds_read2_b32 v[16:17], v2 offset0:195 offset1:203
	ds_read2_b32 v[18:19], v30 offset0:4 offset1:12
	ds_read2_b32 v[20:21], v30 offset0:69 offset1:77
	ds_read2_b32 v[22:23], v30 offset0:134 offset1:142
	ds_read2_b32 v[24:25], v30 offset0:199 offset1:207
	v_lshl_add_u64 v[8:9], v[66:67], 1, v[64:65]
	s_waitcnt lgkmcnt(6)
	v_cvt_pk_bf16_f32 v4, v12, v10
	v_add_u32_e32 v10, v71, v70
	v_sub_u32_e32 v26, v10, v73
	v_ashrrev_i32_e32 v27, 31, v26
	v_lshlrev_b64 v[28:29], 14, v[26:27]
	s_waitcnt lgkmcnt(4)
	v_cvt_pk_bf16_f32 v5, v14, v16
	s_waitcnt lgkmcnt(2)
	v_cvt_pk_bf16_f32 v6, v18, v20
	s_waitcnt lgkmcnt(0)
	v_cvt_pk_bf16_f32 v7, v22, v24
	v_lshl_add_u64 v[28:29], v[8:9], 0, v[28:29]
	v_add_u32_e32 v10, 8, v26
	global_store_dwordx4 v[28:29], v[4:7], off
	v_add_u32_e32 v28, 16, v26
	v_ashrrev_i32_e32 v29, 31, v28
	v_cvt_pk_bf16_f32 v4, v13, v11
	v_ashrrev_i32_e32 v11, 31, v10
	v_lshlrev_b64 v[10:11], 14, v[10:11]
	v_cvt_pk_bf16_f32 v5, v15, v17
	v_cvt_pk_bf16_f32 v6, v19, v21
	v_cvt_pk_bf16_f32 v7, v23, v25
	v_lshl_add_u64 v[10:11], v[8:9], 0, v[10:11]
	global_store_dwordx4 v[10:11], v[4:7], off
	ds_read2_b32 v[10:11], v2 offset0:81 offset1:89
	ds_read2_b32 v[12:13], v2 offset0:16 offset1:24
	ds_read2_b32 v[14:15], v2 offset0:146 offset1:154
	ds_read2_b32 v[16:17], v2 offset0:211 offset1:219
	ds_read2_b32 v[18:19], v30 offset0:20 offset1:28
	ds_read2_b32 v[20:21], v30 offset0:85 offset1:93
	ds_read2_b32 v[22:23], v30 offset0:150 offset1:158
	ds_read2_b32 v[24:25], v30 offset0:215 offset1:223
	v_lshlrev_b64 v[28:29], 14, v[28:29]
	s_waitcnt lgkmcnt(6)
	v_cvt_pk_bf16_f32 v4, v12, v10
	s_waitcnt lgkmcnt(4)
	v_cvt_pk_bf16_f32 v5, v14, v16
	s_waitcnt lgkmcnt(2)
	v_cvt_pk_bf16_f32 v6, v18, v20
	s_waitcnt lgkmcnt(0)
	v_cvt_pk_bf16_f32 v7, v22, v24
	v_lshl_add_u64 v[28:29], v[8:9], 0, v[28:29]
	v_add_u32_e32 v10, 24, v26
	global_store_dwordx4 v[28:29], v[4:7], off
	v_add_u32_e32 v28, 32, v26
	v_ashrrev_i32_e32 v29, 31, v28
	v_cvt_pk_bf16_f32 v4, v13, v11
	v_ashrrev_i32_e32 v11, 31, v10
	v_lshlrev_b64 v[10:11], 14, v[10:11]
	v_cvt_pk_bf16_f32 v5, v15, v17
	v_cvt_pk_bf16_f32 v6, v19, v21
	v_cvt_pk_bf16_f32 v7, v23, v25
	v_lshl_add_u64 v[10:11], v[8:9], 0, v[10:11]
	global_store_dwordx4 v[10:11], v[4:7], off
	ds_read2_b32 v[10:11], v2 offset0:32 offset1:40
	ds_read2_b32 v[12:13], v2 offset0:97 offset1:105
	ds_read2_b32 v[14:15], v2 offset0:162 offset1:170
	ds_read2_b32 v[16:17], v2 offset0:227 offset1:235
	ds_read2_b32 v[18:19], v30 offset0:36 offset1:44
	ds_read2_b32 v[20:21], v30 offset0:101 offset1:109
	ds_read2_b32 v[22:23], v30 offset0:166 offset1:174
	ds_read2_b32 v[24:25], v30 offset0:231 offset1:239
	v_lshlrev_b64 v[28:29], 14, v[28:29]
	s_waitcnt lgkmcnt(6)
	v_cvt_pk_bf16_f32 v4, v10, v12
	s_waitcnt lgkmcnt(4)
	v_cvt_pk_bf16_f32 v5, v14, v16
	s_waitcnt lgkmcnt(2)
	v_cvt_pk_bf16_f32 v6, v18, v20
	s_waitcnt lgkmcnt(0)
	v_cvt_pk_bf16_f32 v7, v22, v24
	v_lshl_add_u64 v[28:29], v[8:9], 0, v[28:29]
	v_add_u32_e32 v10, 40, v26
	global_store_dwordx4 v[28:29], v[4:7], off
	v_add_u32_e32 v28, 48, v26
	v_ashrrev_i32_e32 v29, 31, v28
	v_cvt_pk_bf16_f32 v4, v11, v13
	v_ashrrev_i32_e32 v11, 31, v10
	v_lshlrev_b64 v[10:11], 14, v[10:11]
	v_cvt_pk_bf16_f32 v5, v15, v17
	v_cvt_pk_bf16_f32 v6, v19, v21
	v_cvt_pk_bf16_f32 v7, v23, v25
	v_lshl_add_u64 v[10:11], v[8:9], 0, v[10:11]
	global_store_dwordx4 v[10:11], v[4:7], off
	ds_read2_b32 v[10:11], v2 offset0:48 offset1:56
	ds_read2_b32 v[12:13], v2 offset0:113 offset1:121
	ds_read2_b32 v[14:15], v2 offset0:178 offset1:186
	ds_read2_b32 v[16:17], v2 offset0:243 offset1:251
	ds_read2_b32 v[18:19], v30 offset0:52 offset1:60
	ds_read2_b32 v[20:21], v30 offset0:117 offset1:125
	ds_read2_b32 v[22:23], v30 offset0:182 offset1:190
	ds_read2_b32 v[24:25], v30 offset0:247 offset1:255
	v_lshlrev_b64 v[28:29], 14, v[28:29]
	s_waitcnt lgkmcnt(6)
	v_cvt_pk_bf16_f32 v4, v10, v12
	s_waitcnt lgkmcnt(4)
	v_cvt_pk_bf16_f32 v5, v14, v16
	s_waitcnt lgkmcnt(2)
	v_cvt_pk_bf16_f32 v6, v18, v20
	s_waitcnt lgkmcnt(0)
	v_cvt_pk_bf16_f32 v7, v22, v24
	v_lshl_add_u64 v[28:29], v[8:9], 0, v[28:29]
	v_add_u32_e32 v10, 56, v26
	global_store_dwordx4 v[28:29], v[4:7], off
	v_add_u32_e32 v70, 0x200, v70
	s_nop 0
	v_cvt_pk_bf16_f32 v4, v11, v13
	v_ashrrev_i32_e32 v11, 31, v10
	v_lshlrev_b64 v[10:11], 14, v[10:11]
	v_cvt_pk_bf16_f32 v5, v15, v17
	v_cvt_pk_bf16_f32 v6, v19, v21
	v_cvt_pk_bf16_f32 v7, v23, v25
	v_lshl_add_u64 v[8:9], v[8:9], 0, v[10:11]
	global_store_dwordx4 v[8:9], v[4:7], off
	s_waitcnt lgkmcnt(0)
	s_andn2_b64 exec, exec, s[12:13]
	s_cbranch_execnz .LBB0_1882

;     ...
;         for (int i = 0; i < 16; ++i) { float* d = scr + (4 * i + ksub) * 65 + n4; d[0] = v[i].x; d[1] = v[i].y; d[2] = v[i].z; d[3] = v[i].w; }
;         __builtin_amdgcn_s_waitcnt(0); asm volatile("" ::: "memory");
;         const int c = lane & 7;
.LBB0_1887:
	s_waitcnt vmcnt(15)
	ds_write2_b32 v78, v8, v9 offset1:1
	ds_write2_b32 v78, v10, v11 offset0:2 offset1:3
	v_add_u32_e32 v8, 0x410, v78
	s_waitcnt vmcnt(14)
	ds_write2_b32 v8, v4, v5 offset1:1
	v_add_u32_e32 v4, 0x418, v78
	ds_write2_b32 v4, v6, v7 offset1:1
	v_add_u32_e32 v4, 0x820, v78
	s_waitcnt vmcnt(13)
	ds_write2_b32 v4, v16, v17 offset1:1
	v_add_u32_e32 v4, 0x828, v78
	ds_write2_b32 v4, v18, v19 offset1:1
	v_add_u32_e32 v4, 0xc30, v78
	s_waitcnt vmcnt(12)
	ds_write2_b32 v4, v12, v13 offset1:1
	v_add_u32_e32 v4, 0xc38, v78
	ds_write2_b32 v4, v14, v15 offset1:1
	v_add_u32_e32 v4, 0x1040, v78
	s_waitcnt vmcnt(11)
	ds_write2_b32 v4, v24, v25 offset1:1
	v_add_u32_e32 v4, 0x1048, v78
	ds_write2_b32 v4, v26, v27 offset1:1
	v_add_u32_e32 v4, 0x1450, v78
	s_waitcnt vmcnt(10)
	ds_write2_b32 v4, v20, v21 offset1:1
	v_add_u32_e32 v4, 0x1458, v78
	ds_write2_b32 v4, v22, v23 offset1:1
	v_add_u32_e32 v4, 0x1860, v78
	s_waitcnt vmcnt(9)
	ds_write2_b32 v4, v32, v33 offset1:1
	v_add_u32_e32 v4, 0x1868, v78
	ds_write2_b32 v4, v34, v35 offset1:1
	v_add_u32_e32 v4, 0x1c70, v78
	s_waitcnt vmcnt(8)
	ds_write2_b32 v4, v28, v29 offset1:1
	v_add_u32_e32 v4, 0x1c78, v78
	ds_write2_b32 v4, v30, v31 offset1:1
	v_add_u32_e32 v4, 0x2080, v78
	s_waitcnt vmcnt(7)
	ds_write2_b32 v4, v40, v41 offset1:1
	v_add_u32_e32 v4, 0x2088, v78
	ds_write2_b32 v4, v42, v43 offset1:1
	v_add_u32_e32 v4, 0x2490, v78
	s_waitcnt vmcnt(6)
	ds_write2_b32 v4, v36, v37 offset1:1
	v_add_u32_e32 v4, 0x2498, v78
	ds_write2_b32 v4, v38, v39 offset1:1
	v_add_u32_e32 v4, 0x28a0, v78
	s_waitcnt vmcnt(5)
	ds_write2_b32 v4, v48, v49 offset1:1
	v_add_u32_e32 v4, 0x28a8, v78
	ds_write2_b32 v4, v50, v51 offset1:1
	v_add_u32_e32 v4, 0x2cb0, v78
	s_waitcnt vmcnt(4)
	ds_write2_b32 v4, v44, v45 offset1:1
	v_add_u32_e32 v4, 0x2cb8, v78
	ds_write2_b32 v4, v46, v47 offset1:1
	v_add_u32_e32 v4, 0x30c0, v78
	s_waitcnt vmcnt(3)
	ds_write2_b32 v4, v56, v57 offset1:1
	v_add_u32_e32 v4, 0x30c8, v78
	ds_write2_b32 v4, v58, v59 offset1:1
	v_add_u32_e32 v4, 0x34d0, v78
	s_waitcnt vmcnt(2)
	ds_write2_b32 v4, v52, v53 offset1:1
	v_add_u32_e32 v4, 0x34d8, v78
	ds_write2_b32 v4, v54, v55 offset1:1
	v_add_u32_e32 v4, 0x38e0, v78
	s_waitcnt vmcnt(1)
	ds_write2_b32 v4, v64, v65 offset1:1
	v_add_u32_e32 v4, 0x38e8, v78
	ds_write2_b32 v4, v66, v67 offset1:1
	v_add_u32_e32 v4, 0x3cf0, v78
	s_waitcnt vmcnt(0)
	ds_write2_b32 v4, v60, v61 offset1:1
	v_add_u32_e32 v4, 0x3cf8, v78
	ds_write2_b32 v4, v62, v63 offset1:1
	s_waitcnt vmcnt(0) expcnt(0) lgkmcnt(0)
	v_add_u32_e32 v30, 0x400, v2
	ds_read2_b32 v[8:9], v2 offset0:65 offset1:73
	ds_read2_b32 v[10:11], v2 offset1:8
	ds_read2_b32 v[12:13], v2 offset0:130 offset1:138
	ds_read2_b32 v[14:15], v2 offset0:195 offset1:203
	ds_read2_b32 v[16:17], v30 offset0:4 offset1:12
	ds_read2_b32 v[18:19], v30 offset0:69 offset1:77
	ds_read2_b32 v[20:21], v30 offset0:134 offset1:142
	ds_read2_b32 v[22:23], v30 offset0:199 offset1:207
	v_sub_u32_e32 v72, 0, v71
	v_add3_u32 v26, v77, v76, v72
	v_ashrrev_i32_e32 v71, 31, v70
	v_ashrrev_i32_e32 v27, 31, v26
	v_lshl_add_u64 v[24:25], v[70:71], 1, v[68:69]
	v_lshlrev_b64 v[28:29], 12, v[26:27]
	s_waitcnt lgkmcnt(6)
	v_cvt_pk_bf16_f32 v4, v10, v8
	s_waitcnt lgkmcnt(4)
	v_cvt_pk_bf16_f32 v5, v12, v14
	s_waitcnt lgkmcnt(2)
	v_cvt_pk_bf16_f32 v6, v16, v18
	s_waitcnt lgkmcnt(0)
; __device__ __forceinline__ unsigned pk2(float lo, float hi) { f32x2 v = {lo, hi}; return __builtin_bit_cast(unsigned, __builtin_convertvector(v, bf16x2_hw)); }
;     ...
;         const int c = lane & 7;
; #pragma unroll
;         for (int j = 0; j < 8; ++j) { const int nn = (lane >> 3) + 8 * j; const float* sp = scr + (8 * c) * 65 + nn;
;             u32x4 o; o.x = pk2(sp[0 * 65], sp[1 * 65]); o.y = pk2(sp[2 * 65], sp[3 * 65]); o.z = pk2(sp[4 * 65], sp[5 * 65]); o.w = pk2(sp[6 * 65], sp[7 * 65]);
;             *(u32x4*)(WT + (size_t)(n0 + nn) * K + k0 + 8 * c) = o; }
;         __builtin_amdgcn_s_waitcnt(0); asm volatile("" ::: "memory");
;     }
	v_cvt_pk_bf16_f32 v7, v20, v22
	v_lshl_add_u64 v[28:29], v[24:25], 0, v[28:29]
	v_add_u32_e32 v8, 8, v26
	global_store_dwordx4 v[28:29], v[4:7], off
	v_add_u32_e32 v1, 8, v1
	v_cmp_le_i32_e32 vcc, s3, v1
	v_cvt_pk_bf16_f32 v4, v11, v9
	v_ashrrev_i32_e32 v9, 31, v8
	v_cvt_pk_bf16_f32 v5, v13, v15
	v_cvt_pk_bf16_f32 v6, v17, v19
	v_cvt_pk_bf16_f32 v7, v21, v23
	v_lshlrev_b64 v[8:9], 12, v[8:9]
	ds_read2_b32 v[10:11], v2 offset0:81 offset1:89
	ds_read2_b32 v[12:13], v2 offset0:16 offset1:24
	ds_read2_b32 v[14:15], v2 offset0:146 offset1:154
	ds_read2_b32 v[16:17], v2 offset0:211 offset1:219
	ds_read2_b32 v[18:19], v30 offset0:20 offset1:28
	ds_read2_b32 v[20:21], v30 offset0:85 offset1:93
	ds_read2_b32 v[22:23], v30 offset0:150 offset1:158
	ds_read2_b32 v[28:29], v30 offset0:215 offset1:223
	v_lshl_add_u64 v[8:9], v[24:25], 0, v[8:9]
	global_store_dwordx4 v[8:9], v[4:7], off
	v_add_u32_e32 v8, 16, v26
	v_ashrrev_i32_e32 v9, 31, v8
	v_lshlrev_b64 v[8:9], 12, v[8:9]
	s_waitcnt lgkmcnt(6)
	v_cvt_pk_bf16_f32 v4, v12, v10
	s_waitcnt lgkmcnt(4)
	v_cvt_pk_bf16_f32 v5, v14, v16
	s_waitcnt lgkmcnt(2)
	v_cvt_pk_bf16_f32 v6, v18, v20
	s_waitcnt lgkmcnt(0)
	v_cvt_pk_bf16_f32 v7, v22, v28
	v_lshl_add_u64 v[8:9], v[24:25], 0, v[8:9]
	global_store_dwordx4 v[8:9], v[4:7], off
	v_add_u32_e32 v8, 24, v26
	v_ashrrev_i32_e32 v9, 31, v8
	v_cvt_pk_bf16_f32 v4, v13, v11
	v_cvt_pk_bf16_f32 v5, v15, v17
	v_cvt_pk_bf16_f32 v6, v19, v21
	v_cvt_pk_bf16_f32 v7, v23, v29
	v_lshlrev_b64 v[8:9], 12, v[8:9]
	ds_read2_b32 v[10:11], v2 offset0:32 offset1:40
	ds_read2_b32 v[12:13], v2 offset0:97 offset1:105
	ds_read2_b32 v[14:15], v2 offset0:162 offset1:170
	ds_read2_b32 v[16:17], v2 offset0:227 offset1:235
	ds_read2_b32 v[18:19], v30 offset0:36 offset1:44
	ds_read2_b32 v[20:21], v30 offset0:101 offset1:109
	ds_read2_b32 v[22:23], v30 offset0:166 offset1:174
	ds_read2_b32 v[28:29], v30 offset0:231 offset1:239
	v_lshl_add_u64 v[8:9], v[24:25], 0, v[8:9]
	global_store_dwordx4 v[8:9], v[4:7], off
	v_add_u32_e32 v8, 32, v26
	v_ashrrev_i32_e32 v9, 31, v8
	v_lshlrev_b64 v[8:9], 12, v[8:9]
	s_waitcnt lgkmcnt(6)
	v_cvt_pk_bf16_f32 v4, v10, v12
	s_waitcnt lgkmcnt(4)
	v_cvt_pk_bf16_f32 v5, v14, v16
	s_waitcnt lgkmcnt(2)
	v_cvt_pk_bf16_f32 v6, v18, v20
	s_waitcnt lgkmcnt(0)
	v_cvt_pk_bf16_f32 v7, v22, v28
	v_lshl_add_u64 v[8:9], v[24:25], 0, v[8:9]
	global_store_dwordx4 v[8:9], v[4:7], off
	v_add_u32_e32 v8, 40, v26
	v_ashrrev_i32_e32 v9, 31, v8
	v_cvt_pk_bf16_f32 v4, v11, v13
	v_cvt_pk_bf16_f32 v5, v15, v17
	v_cvt_pk_bf16_f32 v6, v19, v21
	v_cvt_pk_bf16_f32 v7, v23, v29
	v_lshlrev_b64 v[8:9], 12, v[8:9]
	ds_read2_b32 v[10:11], v2 offset0:48 offset1:56
	ds_read2_b32 v[12:13], v2 offset0:113 offset1:121
	ds_read2_b32 v[14:15], v2 offset0:178 offset1:186
	ds_read2_b32 v[16:17], v2 offset0:243 offset1:251
	ds_read2_b32 v[18:19], v30 offset0:52 offset1:60
	ds_read2_b32 v[20:21], v30 offset0:117 offset1:125
	ds_read2_b32 v[22:23], v30 offset0:182 offset1:190
	ds_read2_b32 v[28:29], v30 offset0:247 offset1:255
	v_lshl_add_u64 v[8:9], v[24:25], 0, v[8:9]
	global_store_dwordx4 v[8:9], v[4:7], off
	v_add_u32_e32 v8, 48, v26
	v_ashrrev_i32_e32 v9, 31, v8
	v_lshlrev_b64 v[8:9], 12, v[8:9]
	s_waitcnt lgkmcnt(6)
	v_cvt_pk_bf16_f32 v4, v10, v12
	s_waitcnt lgkmcnt(4)
	v_cvt_pk_bf16_f32 v5, v14, v16
	s_waitcnt lgkmcnt(2)
	v_cvt_pk_bf16_f32 v6, v18, v20
	s_waitcnt lgkmcnt(0)
	v_cvt_pk_bf16_f32 v7, v22, v28
	v_lshl_add_u64 v[8:9], v[24:25], 0, v[8:9]
	global_store_dwordx4 v[8:9], v[4:7], off
	v_add_u32_e32 v8, 56, v26
	v_ashrrev_i32_e32 v9, 31, v8
	v_lshlrev_b64 v[8:9], 12, v[8:9]
	v_cvt_pk_bf16_f32 v4, v11, v13
	v_cvt_pk_bf16_f32 v5, v15, v17
	v_cvt_pk_bf16_f32 v6, v19, v21
	v_cvt_pk_bf16_f32 v7, v23, v29
	v_lshl_add_u64 v[8:9], v[24:25], 0, v[8:9]
	global_store_dwordx4 v[8:9], v[4:7], off
	s_waitcnt lgkmcnt(0)
	v_add_u32_e32 v76, 0x200, v76
	s_or_b64 s[14:15], vcc, s[14:15]
	v_add_u32_e32 v75, 0x200, v75
	s_andn2_b64 exec, exec, s[14:15]
	s_cbranch_execz .LBB0_1890

;     ...
;     for (int it = it_lo; it < it_hi; it += it_st) {
;         const int kb = it / nblk, nb = it % nblk, k0 = 64 * kb, n0 = 64 * nb;
;         const int ng = n0 + n4; const int no = MAP ? win_map(ng) : ng;
;         const bool vec = MAP ? (no >= 0 && win_map(ng + 3) == no + 3) : true;
;         f32x4 v[16];
;         if (vec) {
; #pragma unroll
;             for (int i = 0; i < 16; ++i) { const float* p = W + (size_t)(k0 + 4 * i + ksub) * N_orig + no; if (MAP) { const f32x2 a0 = *(const f32x2*)p, a1 = *(const f32x2*)(p + 2); v[i] = (f32x4){a0.x, a0.y, a1.x, a1.y}; }
;                 else v[i] = __builtin_nontemporal_load((const f32x4*)p); }
;         } else {
; #pragma unroll
;             for (int i = 0; i < 16; ++i) { const float* p = W + (size_t)(k0 + 4 * i + ksub) * N_orig;
; #pragma unroll
;                 for (int e = 0; e < 4; ++e) { const int ne = MAP ? win_map(ng + e) : ng + e; v[i][e] = ne >= 0 ? p[ne] : 0.f; } }
;         }
;         if (kscale) {
; #pragma unroll
;             for (int i = 0; i < 16; ++i) v[i] *= kscale[k0 + 4 * i + ksub]; }
; #pragma unroll
;         for (int i = 0; i < 16; ++i) { float* d = scr + (4 * i + ksub) * 65 + n4; d[0] = v[i].x; d[1] = v[i].y; d[2] = v[i].z; d[3] = v[i].w; }
.LBB0_1895:
	v_ashrrev_i32_e32 v4, 31, v1
	v_lshrrev_b32_e32 v4, 27, v4
	v_add_u32_e32 v4, v1, v4
	v_ashrrev_i32_e32 v4, 5, v4
	v_lshlrev_b32_e32 v66, 6, v4
	v_lshlrev_b32_e32 v73, 11, v4
	v_add_u32_e32 v4, v71, v69
	v_sub_u32_e32 v4, v4, v73
	v_or_b32_e32 v6, v66, v68
	v_ashrrev_i32_e32 v5, 31, v4
	v_ashrrev_i32_e32 v7, 31, v6
	v_lshl_add_u64 v[4:5], v[4:5], 2, s[10:11]
	v_lshlrev_b64 v[8:9], 13, v[6:7]
	v_lshl_add_u64 v[8:9], v[4:5], 0, v[8:9]
	global_load_dwordx4 v[74:77], v[8:9], off nt
	v_or_b32_e32 v8, 4, v6
	v_ashrrev_i32_e32 v9, 31, v8
	v_lshlrev_b64 v[8:9], 13, v[8:9]
	v_lshl_add_u64 v[8:9], v[4:5], 0, v[8:9]
	global_load_dwordx4 v[60:63], v[8:9], off nt
	v_or_b32_e32 v8, 8, v6
	v_ashrrev_i32_e32 v9, 31, v8
	v_lshlrev_b64 v[8:9], 13, v[8:9]
	v_lshl_add_u64 v[8:9], v[4:5], 0, v[8:9]
	global_load_dwordx4 v[56:59], v[8:9], off nt
	v_or_b32_e32 v8, 12, v6
	v_ashrrev_i32_e32 v9, 31, v8
	v_lshlrev_b64 v[8:9], 13, v[8:9]
	v_lshl_add_u64 v[8:9], v[4:5], 0, v[8:9]
	global_load_dwordx4 v[52:55], v[8:9], off nt
	v_or_b32_e32 v8, 16, v6
	v_ashrrev_i32_e32 v9, 31, v8
	v_lshlrev_b64 v[8:9], 13, v[8:9]
	v_lshl_add_u64 v[8:9], v[4:5], 0, v[8:9]
	global_load_dwordx4 v[48:51], v[8:9], off nt
	v_or_b32_e32 v8, 20, v6
	v_ashrrev_i32_e32 v9, 31, v8
	v_lshlrev_b64 v[8:9], 13, v[8:9]
	v_lshl_add_u64 v[8:9], v[4:5], 0, v[8:9]
	global_load_dwordx4 v[44:47], v[8:9], off nt
	v_or_b32_e32 v8, 24, v6
	v_ashrrev_i32_e32 v9, 31, v8
	v_lshlrev_b64 v[8:9], 13, v[8:9]
	v_lshl_add_u64 v[8:9], v[4:5], 0, v[8:9]
	global_load_dwordx4 v[40:43], v[8:9], off nt
	v_or_b32_e32 v8, 28, v6
	v_ashrrev_i32_e32 v9, 31, v8
	v_lshlrev_b64 v[8:9], 13, v[8:9]
	v_lshl_add_u64 v[8:9], v[4:5], 0, v[8:9]
	global_load_dwordx4 v[36:39], v[8:9], off nt
	v_or_b32_e32 v8, 32, v6
	v_ashrrev_i32_e32 v9, 31, v8
	v_lshlrev_b64 v[8:9], 13, v[8:9]
	v_lshl_add_u64 v[8:9], v[4:5], 0, v[8:9]
	global_load_dwordx4 v[32:35], v[8:9], off nt
	v_or_b32_e32 v8, 36, v6
	v_ashrrev_i32_e32 v9, 31, v8
	v_lshlrev_b64 v[8:9], 13, v[8:9]
	v_lshl_add_u64 v[8:9], v[4:5], 0, v[8:9]
	global_load_dwordx4 v[28:31], v[8:9], off nt
	v_or_b32_e32 v8, 40, v6
	v_ashrrev_i32_e32 v9, 31, v8
	v_lshlrev_b64 v[8:9], 13, v[8:9]
	v_lshl_add_u64 v[8:9], v[4:5], 0, v[8:9]
	global_load_dwordx4 v[24:27], v[8:9], off nt
	v_or_b32_e32 v8, 44, v6
	v_ashrrev_i32_e32 v9, 31, v8
	v_lshlrev_b64 v[8:9], 13, v[8:9]
	v_lshl_add_u64 v[8:9], v[4:5], 0, v[8:9]
	global_load_dwordx4 v[20:23], v[8:9], off nt
	v_or_b32_e32 v8, 48, v6
	v_ashrrev_i32_e32 v9, 31, v8
	v_lshlrev_b64 v[8:9], 13, v[8:9]
	v_lshl_add_u64 v[8:9], v[4:5], 0, v[8:9]
	global_load_dwordx4 v[16:19], v[8:9], off nt
	v_or_b32_e32 v8, 52, v6
	v_ashrrev_i32_e32 v9, 31, v8
	v_lshlrev_b64 v[8:9], 13, v[8:9]
	v_lshl_add_u64 v[8:9], v[4:5], 0, v[8:9]
	global_load_dwordx4 v[12:15], v[8:9], off nt
	v_or_b32_e32 v8, 56, v6
	v_ashrrev_i32_e32 v9, 31, v8
	v_lshlrev_b64 v[8:9], 13, v[8:9]
	v_or_b32_e32 v6, 60, v6
	v_lshl_add_u64 v[8:9], v[4:5], 0, v[8:9]
	v_ashrrev_i32_e32 v7, 31, v6
	global_load_dwordx4 v[8:11], v[8:9], off nt
	v_lshlrev_b64 v[6:7], 13, v[6:7]
	v_lshl_add_u64 v[4:5], v[4:5], 0, v[6:7]
	global_load_dwordx4 v[4:7], v[4:5], off nt
	v_add_u32_e32 v67, 0x410, v72
	s_waitcnt vmcnt(15)
	ds_write2_b32 v72, v74, v75 offset1:1
	ds_write2_b32 v72, v76, v77 offset0:2 offset1:3
	v_add_u32_e32 v1, s3, v1
	v_cmp_le_i32_e32 vcc, s2, v1
	v_add_u32_e32 v69, s12, v69
	s_or_b64 s[6:7], vcc, s[6:7]
	s_waitcnt vmcnt(14)
	ds_write2_b32 v67, v60, v61 offset1:1
	v_add_u32_e32 v60, 0x418, v72
	ds_write2_b32 v60, v62, v63 offset1:1
	v_add_u32_e32 v60, 0x820, v72
	v_ashrrev_i32_e32 v67, 31, v66
	s_waitcnt vmcnt(13)
	ds_write2_b32 v60, v56, v57 offset1:1
	v_add_u32_e32 v56, 0x828, v72
	ds_write2_b32 v56, v58, v59 offset1:1
	v_add_u32_e32 v56, 0xc30, v72
	s_waitcnt vmcnt(12)
	ds_write2_b32 v56, v52, v53 offset1:1
	v_add_u32_e32 v52, 0xc38, v72
	ds_write2_b32 v52, v54, v55 offset1:1
	v_add_u32_e32 v52, 0x1040, v72
	s_waitcnt vmcnt(11)
	ds_write2_b32 v52, v48, v49 offset1:1
	v_add_u32_e32 v48, 0x1048, v72
	ds_write2_b32 v48, v50, v51 offset1:1
	v_add_u32_e32 v48, 0x1450, v72
	s_waitcnt vmcnt(10)
	ds_write2_b32 v48, v44, v45 offset1:1
	v_add_u32_e32 v44, 0x1458, v72
	ds_write2_b32 v44, v46, v47 offset1:1
	v_add_u32_e32 v44, 0x1860, v72
	s_waitcnt vmcnt(9)
	ds_write2_b32 v44, v40, v41 offset1:1
	v_add_u32_e32 v40, 0x1868, v72
	ds_write2_b32 v40, v42, v43 offset1:1
	v_add_u32_e32 v40, 0x1c70, v72
	s_waitcnt vmcnt(8)
	ds_write2_b32 v40, v36, v37 offset1:1
	v_add_u32_e32 v36, 0x1c78, v72
	ds_write2_b32 v36, v38, v39 offset1:1
	v_add_u32_e32 v36, 0x2080, v72
	s_waitcnt vmcnt(7)
	ds_write2_b32 v36, v32, v33 offset1:1
	v_add_u32_e32 v32, 0x2088, v72
	ds_write2_b32 v32, v34, v35 offset1:1
	v_add_u32_e32 v32, 0x2490, v72
	s_waitcnt vmcnt(6)
	ds_write2_b32 v32, v28, v29 offset1:1
	v_add_u32_e32 v28, 0x2498, v72
	ds_write2_b32 v28, v30, v31 offset1:1
	v_add_u32_e32 v28, 0x28a0, v72
	v_add_u32_e32 v30, 0x400, v2
	s_waitcnt vmcnt(5)
	ds_write2_b32 v28, v24, v25 offset1:1
	v_add_u32_e32 v24, 0x28a8, v72
	ds_write2_b32 v24, v26, v27 offset1:1
	v_add_u32_e32 v24, 0x2cb0, v72
	s_waitcnt vmcnt(4)
	ds_write2_b32 v24, v20, v21 offset1:1
	v_add_u32_e32 v20, 0x2cb8, v72
	ds_write2_b32 v20, v22, v23 offset1:1
	v_add_u32_e32 v20, 0x30c0, v72
	s_waitcnt vmcnt(3)
; __device__ __forceinline__ unsigned pk2(float lo, float hi) { f32x2 v = {lo, hi}; return __builtin_bit_cast(unsigned, __builtin_convertvector(v, bf16x2_hw)); }
;     ...
;         for (int i = 0; i < 16; ++i) { float* d = scr + (4 * i + ksub) * 65 + n4; d[0] = v[i].x; d[1] = v[i].y; d[2] = v[i].z; d[3] = v[i].w; }
;         __builtin_amdgcn_s_waitcnt(0); asm volatile("" ::: "memory");
;         const int c = lane & 7;
; #pragma unroll
;         for (int j = 0; j < 8; ++j) { const int nn = (lane >> 3) + 8 * j; const float* sp = scr + (8 * c) * 65 + nn;
;             u32x4 o; o.x = pk2(sp[0 * 65], sp[1 * 65]); o.y = pk2(sp[2 * 65], sp[3 * 65]); o.z = pk2(sp[4 * 65], sp[5 * 65]); o.w = pk2(sp[6 * 65], sp[7 * 65]);
;             *(u32x4*)(WT + (size_t)(n0 + nn) * K + k0 + 8 * c) = o; }
;         __builtin_amdgcn_s_waitcnt(0); asm volatile("" ::: "memory");
;     }
	ds_write2_b32 v20, v16, v17 offset1:1
	v_add_u32_e32 v16, 0x30c8, v72
	ds_write2_b32 v16, v18, v19 offset1:1
	v_add_u32_e32 v16, 0x34d0, v72
	s_waitcnt vmcnt(2)
	ds_write2_b32 v16, v12, v13 offset1:1
	v_add_u32_e32 v12, 0x34d8, v72
	ds_write2_b32 v12, v14, v15 offset1:1
	v_add_u32_e32 v12, 0x38e0, v72
	s_waitcnt vmcnt(1)
	ds_write2_b32 v12, v8, v9 offset1:1
	v_add_u32_e32 v8, 0x38e8, v72
	ds_write2_b32 v8, v10, v11 offset1:1
	v_add_u32_e32 v8, 0x3cf0, v72
	s_waitcnt vmcnt(0)
	ds_write2_b32 v8, v4, v5 offset1:1
	v_add_u32_e32 v4, 0x3cf8, v72
	ds_write2_b32 v4, v6, v7 offset1:1
	s_waitcnt vmcnt(0) expcnt(0) lgkmcnt(0)
	ds_read2_b32 v[10:11], v2 offset0:65 offset1:73
	ds_read2_b32 v[12:13], v2 offset1:8
	ds_read2_b32 v[14:15], v2 offset0:130 offset1:138
	ds_read2_b32 v[16:17], v2 offset0:195 offset1:203
	ds_read2_b32 v[18:19], v30 offset0:4 offset1:12
	ds_read2_b32 v[20:21], v30 offset0:69 offset1:77
	ds_read2_b32 v[22:23], v30 offset0:134 offset1:142
	ds_read2_b32 v[24:25], v30 offset0:199 offset1:207
	v_lshl_add_u64 v[8:9], v[66:67], 1, v[64:65]
	s_waitcnt lgkmcnt(6)
	v_cvt_pk_bf16_f32 v4, v12, v10
	v_add_u32_e32 v10, v71, v70
	v_sub_u32_e32 v26, v10, v73
	v_ashrrev_i32_e32 v27, 31, v26
	v_lshlrev_b64 v[28:29], 12, v[26:27]
	s_waitcnt lgkmcnt(4)
	v_cvt_pk_bf16_f32 v5, v14, v16
	s_waitcnt lgkmcnt(2)
	v_cvt_pk_bf16_f32 v6, v18, v20
	s_waitcnt lgkmcnt(0)
	v_cvt_pk_bf16_f32 v7, v22, v24
	v_lshl_add_u64 v[28:29], v[8:9], 0, v[28:29]
	v_add_u32_e32 v10, 8, v26
	global_store_dwordx4 v[28:29], v[4:7], off
	v_add_u32_e32 v28, 16, v26
	v_ashrrev_i32_e32 v29, 31, v28
	v_cvt_pk_bf16_f32 v4, v13, v11
	v_ashrrev_i32_e32 v11, 31, v10
	v_lshlrev_b64 v[10:11], 12, v[10:11]
	v_cvt_pk_bf16_f32 v5, v15, v17
	v_cvt_pk_bf16_f32 v6, v19, v21
	v_cvt_pk_bf16_f32 v7, v23, v25
	v_lshl_add_u64 v[10:11], v[8:9], 0, v[10:11]
	global_store_dwordx4 v[10:11], v[4:7], off
	ds_read2_b32 v[10:11], v2 offset0:81 offset1:89
	ds_read2_b32 v[12:13], v2 offset0:16 offset1:24
	ds_read2_b32 v[14:15], v2 offset0:146 offset1:154
	ds_read2_b32 v[16:17], v2 offset0:211 offset1:219
	ds_read2_b32 v[18:19], v30 offset0:20 offset1:28
	ds_read2_b32 v[20:21], v30 offset0:85 offset1:93
	ds_read2_b32 v[22:23], v30 offset0:150 offset1:158
	ds_read2_b32 v[24:25], v30 offset0:215 offset1:223
	v_lshlrev_b64 v[28:29], 12, v[28:29]
	s_waitcnt lgkmcnt(6)
	v_cvt_pk_bf16_f32 v4, v12, v10
	s_waitcnt lgkmcnt(4)
	v_cvt_pk_bf16_f32 v5, v14, v16
	s_waitcnt lgkmcnt(2)
	v_cvt_pk_bf16_f32 v6, v18, v20
	s_waitcnt lgkmcnt(0)
	v_cvt_pk_bf16_f32 v7, v22, v24
	v_lshl_add_u64 v[28:29], v[8:9], 0, v[28:29]
	v_add_u32_e32 v10, 24, v26
	global_store_dwordx4 v[28:29], v[4:7], off
	v_add_u32_e32 v28, 32, v26
	v_ashrrev_i32_e32 v29, 31, v28
	v_cvt_pk_bf16_f32 v4, v13, v11
	v_ashrrev_i32_e32 v11, 31, v10
	v_lshlrev_b64 v[10:11], 12, v[10:11]
	v_cvt_pk_bf16_f32 v5, v15, v17
	v_cvt_pk_bf16_f32 v6, v19, v21
	v_cvt_pk_bf16_f32 v7, v23, v25
	v_lshl_add_u64 v[10:11], v[8:9], 0, v[10:11]
	global_store_dwordx4 v[10:11], v[4:7], off
	ds_read2_b32 v[10:11], v2 offset0:32 offset1:40
	ds_read2_b32 v[12:13], v2 offset0:97 offset1:105
	ds_read2_b32 v[14:15], v2 offset0:162 offset1:170
	ds_read2_b32 v[16:17], v2 offset0:227 offset1:235
	ds_read2_b32 v[18:19], v30 offset0:36 offset1:44
	ds_read2_b32 v[20:21], v30 offset0:101 offset1:109
	ds_read2_b32 v[22:23], v30 offset0:166 offset1:174
	ds_read2_b32 v[24:25], v30 offset0:231 offset1:239
	v_lshlrev_b64 v[28:29], 12, v[28:29]
	s_waitcnt lgkmcnt(6)
	v_cvt_pk_bf16_f32 v4, v10, v12
	s_waitcnt lgkmcnt(4)
	v_cvt_pk_bf16_f32 v5, v14, v16
	s_waitcnt lgkmcnt(2)
	v_cvt_pk_bf16_f32 v6, v18, v20
	s_waitcnt lgkmcnt(0)
	v_cvt_pk_bf16_f32 v7, v22, v24
	v_lshl_add_u64 v[28:29], v[8:9], 0, v[28:29]
	v_add_u32_e32 v10, 40, v26
	global_store_dwordx4 v[28:29], v[4:7], off
	v_add_u32_e32 v28, 48, v26
	v_ashrrev_i32_e32 v29, 31, v28
	v_cvt_pk_bf16_f32 v4, v11, v13
	v_ashrrev_i32_e32 v11, 31, v10
	v_lshlrev_b64 v[10:11], 12, v[10:11]
	v_cvt_pk_bf16_f32 v5, v15, v17
	v_cvt_pk_bf16_f32 v6, v19, v21
	v_cvt_pk_bf16_f32 v7, v23, v25
	v_lshl_add_u64 v[10:11], v[8:9], 0, v[10:11]
	global_store_dwordx4 v[10:11], v[4:7], off
	ds_read2_b32 v[10:11], v2 offset0:48 offset1:56
	ds_read2_b32 v[12:13], v2 offset0:113 offset1:121
	ds_read2_b32 v[14:15], v2 offset0:178 offset1:186
	ds_read2_b32 v[16:17], v2 offset0:243 offset1:251
	ds_read2_b32 v[18:19], v30 offset0:52 offset1:60
	ds_read2_b32 v[20:21], v30 offset0:117 offset1:125
	ds_read2_b32 v[22:23], v30 offset0:182 offset1:190
	ds_read2_b32 v[24:25], v30 offset0:247 offset1:255
	v_lshlrev_b64 v[28:29], 12, v[28:29]
	s_waitcnt lgkmcnt(6)
	v_cvt_pk_bf16_f32 v4, v10, v12
	s_waitcnt lgkmcnt(4)
	v_cvt_pk_bf16_f32 v5, v14, v16
	s_waitcnt lgkmcnt(2)
	v_cvt_pk_bf16_f32 v6, v18, v20
	s_waitcnt lgkmcnt(0)
	v_cvt_pk_bf16_f32 v7, v22, v24
	v_lshl_add_u64 v[28:29], v[8:9], 0, v[28:29]
	v_add_u32_e32 v10, 56, v26
	global_store_dwordx4 v[28:29], v[4:7], off
	v_add_u32_e32 v70, s12, v70
	s_nop 0
	v_cvt_pk_bf16_f32 v4, v11, v13
	v_ashrrev_i32_e32 v11, 31, v10
	v_lshlrev_b64 v[10:11], 12, v[10:11]
	v_cvt_pk_bf16_f32 v5, v15, v17
	v_cvt_pk_bf16_f32 v6, v19, v21
	v_cvt_pk_bf16_f32 v7, v23, v25
	v_lshl_add_u64 v[8:9], v[8:9], 0, v[10:11]
	global_store_dwordx4 v[8:9], v[4:7], off
	s_waitcnt lgkmcnt(0)
	s_andn2_b64 exec, exec, s[6:7]
	s_cbranch_execnz .LBB0_1895
	s_branch .LBB0_1870
